# unpk_attn
# baseline (speedup 1.0000x reference)
; #define MFMA(a, b, c) __builtin_amdgcn_mfma_f32_16x16x32_bf16((a), (b), (c), 0, 0, 0)
; __device__ void phase_attn(const Params& p, char* smem) {
;     ...
;         const int kbase = kt * 32;
;         const int knext = (kt > 0 ? kt - 1 : 0) * 32;
;         bf16x8 kfn[2][2], vf[4];
; #pragma unroll
;         for (int n = 0; n < 2; ++n)
; #pragma unroll
;           for (int ks = 0; ks < 2; ++ks)
;             kfn[n][ks] = *(const bf16x8*)(qk + (size_t)(b * S + knext + n * 16 + l15) * 1024 + 512 + h * 64 + ks * 32 + lq * 8);
; #pragma unroll
;         for (int nn = 0; nn < 4; ++nn)
;           vf[nn] = *(const bf16x8*)(vT + (size_t)(b * 512 + h * 64 + nn * 16 + l15) * S + kbase + lq * 8);
;         f32x4 s[2][2];
;         __builtin_amdgcn_s_setprio(1);
; #pragma unroll
;         for (int n = 0; n < 2; ++n) {
;           s[0][n] = f32x4{0.f, 0.f, 0.f, 0.f};
;           s[1][n] = f32x4{0.f, 0.f, 0.f, 0.f};
; #pragma unroll
;           for (int ks = 0; ks < 2; ++ks) {
;             s[0][n] = MFMA(qf[0][ks], kfc[n][ks], s[0][n]);
;             s[1][n] = MFMA(qf[1][ks], kfc[n][ks], s[1][n]);
;           }
;         }
;         __builtin_amdgcn_s_setprio(0);
;     ...
;         if (kbase + 31 >= q0) { ATT_TILE(true) } else { ATT_TILE(false) }
.LBB0_225:
	s_waitcnt vmcnt(3)
	v_mov_b64_e32 v[90:91], v[50:51]
	s_min_u32 s6, s74, 1
	s_waitcnt vmcnt(1)
	v_mov_b64_e32 v[94:95], v[58:59]
	v_mov_b64_e32 v[88:89], v[48:49]
	v_add_u32_e32 v48, s73, v201
	s_lshl_b32 s6, s6, 5
	v_mov_b64_e32 v[92:93], v[56:57]
	v_subrev_u32_e32 v56, s6, v48
	v_subrev_u32_e32 v48, 31, v56
	v_add_u32_e32 v56, -15, v56
	v_ashrrev_i32_e32 v49, 31, v48
	v_ashrrev_i32_e32 v57, 31, v56
	s_sub_i32 s36, s73, 31
	s_waitcnt vmcnt(0)
	v_mov_b64_e32 v[86:87], v[62:63]
	v_mov_b64_e32 v[82:83], v[54:55]
	v_lshlrev_b64 v[48:49], 11, v[48:49]
	v_lshlrev_b64 v[56:57], 11, v[56:57]
	v_lshl_add_u64 v[72:73], s[36:37], 1, v[134:135]
	v_mov_b64_e32 v[84:85], v[60:61]
	v_mov_b64_e32 v[80:81], v[52:53]
	v_lshl_add_u64 v[52:53], v[142:143], 0, v[48:49]
	v_lshl_add_u64 v[60:61], v[142:143], 0, v[56:57]
	v_lshl_add_u64 v[64:65], v[72:73], 0, v[104:105]
	v_lshl_add_u64 v[66:67], v[72:73], 0, v[106:107]
	v_lshl_add_u64 v[74:75], v[72:73], 0, v[108:109]
	v_lshl_add_u64 v[72:73], v[72:73], 0, v[110:111]
	global_load_dwordx4 v[48:51], v[52:53], off offset:1024
	s_nop 0
	global_load_dwordx4 v[52:55], v[52:53], off offset:1088
	s_nop 0
	global_load_dwordx4 v[56:59], v[60:61], off offset:1024
	s_nop 0
	global_load_dwordx4 v[60:63], v[60:61], off offset:1088
	s_nop 0
	global_load_dwordx4 v[68:71], v[64:65], off
	s_nop 0
	global_load_dwordx4 v[64:67], v[66:67], off
	s_nop 0
	global_load_dwordx4 v[76:79], v[74:75], off
	s_nop 0
	global_load_dwordx4 v[72:75], v[72:73], off
	s_setprio 1
	v_mfma_f32_16x16x32_bf16 v[122:125], v[32:35], v[88:91], 0
	v_mfma_f32_16x16x32_bf16 v[158:161], v[40:43], v[88:91], 0
	v_mfma_f32_16x16x32_bf16 v[88:91], v[36:39], v[80:83], v[122:125]
	v_mfma_f32_16x16x32_bf16 v[80:83], v[44:47], v[80:83], v[158:161]
	v_mfma_f32_16x16x32_bf16 v[122:125], v[32:35], v[92:95], 0
	v_mfma_f32_16x16x32_bf16 v[158:161], v[40:43], v[92:95], 0
	v_mfma_f32_16x16x32_bf16 v[92:95], v[36:39], v[84:87], v[122:125]
	v_mfma_f32_16x16x32_bf16 v[84:87], v[44:47], v[84:87], v[158:161]
	s_setprio 0
	s_cmp_ge_u32 s73, s70
	s_mov_b64 s[6:7], -1
	s_cbranch_scc0 .LBB0_227
	s_nop 2
	v_mul_f32_e32 v118, 0x3e38aa3b, v92
	v_exp_f32_e64 v119, -|v118|
	v_add_u32_e32 v122, s73, v151
	v_mul_f32_e32 v123, 0x3e38aa3b, v93
	v_subrev_u32_e32 v126, 31, v122
	v_add_f32_e32 v119, 1.0, v119
	v_log_f32_e32 v119, v119
	v_add_u32_e32 v127, -15, v122
	v_exp_f32_e64 v122, -|v123|
	v_max_f32_e64 v118, -v118, 0
	v_add_f32_e32 v118, v118, v119
	v_fma_f32 v124, v92, s41, -v118
	v_sub_f32_e32 v133, v120, v118
	v_add_f32_e32 v118, 1.0, v122
	v_log_f32_e32 v118, v118
	v_mul_f32_e32 v122, 0x3e38aa3b, v88
	v_max_f32_e64 v119, -v123, 0
	v_exp_f32_e64 v123, -|v122|
	v_add_f32_e32 v118, v119, v118
	v_fma_f32 v119, v93, s41, -v118
	v_sub_f32_e32 v157, v121, v118
	v_add_f32_e32 v118, 1.0, v123
	v_mul_f32_e32 v123, 0x3e38aa3b, v89
	v_log_f32_e32 v118, v118
	v_exp_f32_e64 v125, -|v123|
	v_max_f32_e64 v122, -v122, 0
	v_cmp_lt_u32_e32 vcc, v148, v127
	v_add_f32_e32 v163, v122, v118
	v_add_f32_e32 v118, 1.0, v125
	v_cmp_lt_u32_e64 s[6:7], v127, v148
	v_log_f32_e32 v164, v118
	v_cndmask_b32_e64 v119, v119, 0, vcc
	v_cndmask_b32_e64 v118, 0, v124, s[6:7]
	v_max_f32_e64 v161, -v123, 0
	v_mov_b32_dpp v123, v119 quad_perm:[1,0,3,2] row_mask:0xf bank_mask:0xf bound_ctrl:1
	v_mov_b32_dpp v122, v118 quad_perm:[1,0,3,2] row_mask:0xf bank_mask:0xf bound_ctrl:1
	v_add_f32_e32 v118, v118, v122
	v_add_f32_e32 v119, v119, v123
	v_fma_f32 v165, v122, v153, 0
	v_fma_f32 v123, v123, v153, 0
	v_mov_b32_dpp v124, v118 quad_perm:[2,3,0,1] row_mask:0xf bank_mask:0xf bound_ctrl:1
	v_mov_b32_dpp v125, v119 quad_perm:[2,3,0,1] row_mask:0xf bank_mask:0xf bound_ctrl:1
	v_add_f32_e32 v118, v118, v124
	v_add_f32_e32 v119, v119, v125
	v_fmac_f32_e32 v165, v124, v155
	v_fmac_f32_e32 v123, v125, v155
	v_mov_b32_dpp v158, v118 row_half_mirror row_mask:0xf bank_mask:0xf bound_ctrl:1
	v_mov_b32_dpp v159, v119 row_half_mirror row_mask:0xf bank_mask:0xf bound_ctrl:1
	v_add_f32_e32 v118, v118, v158
	v_add_f32_e32 v119, v119, v159
	v_fmac_f32_e32 v165, v158, v180
	v_fmac_f32_e32 v123, v159, v180
	v_mov_b32_dpp v160, v118 row_ror:8 row_mask:0xf bank_mask:0xf bound_ctrl:1
	v_fmac_f32_e32 v165, v160, v181
	v_add_f32_e32 v122, v133, v165
	v_add_f32_e32 v133, v161, v164
	v_mov_b32_dpp v161, v119 row_ror:8 row_mask:0xf bank_mask:0xf bound_ctrl:1
	v_exp_f32_e32 v122, v122
	v_fmac_f32_e32 v123, v161, v181
	v_add_f32_e32 v123, v157, v123
	v_exp_f32_e32 v123, v123
	v_cvt_pk_bf16_f32 v122, v122, s0
	v_cndmask_b32_e64 v122, 0, v122, s[6:7]
	ds_write_b16 v196, v122 offset:32
	v_cvt_pk_bf16_f32 v122, v123, s0
	v_fma_f32 v162, v88, s41, -v163
	v_fma_f32 v124, v89, s41, -v133
	v_cndmask_b32_e64 v157, v122, 0, vcc
	v_cmp_lt_u32_e64 s[6:7], v148, v126
	v_cmp_lt_u32_e32 vcc, v126, v148
	v_add_f32_e32 v118, v118, v160
	v_add_f32_e32 v119, v119, v161
	v_cndmask_b32_e64 v123, v124, 0, s[6:7]
	v_cndmask_b32_e32 v122, 0, v162, vcc
	v_add_f32_e32 v118, v120, v118
	v_add_f32_e32 v119, v121, v119
	v_mov_b32_dpp v125, v123 quad_perm:[1,0,3,2] row_mask:0xf bank_mask:0xf bound_ctrl:1
	v_mov_b32_dpp v124, v122 quad_perm:[1,0,3,2] row_mask:0xf bank_mask:0xf bound_ctrl:1
	v_add_f32_e32 v122, v122, v124
	v_add_f32_e32 v123, v123, v125
	v_fma_f32 v164, v124, v153, 0
	v_sub_f32_e32 v124, v118, v163
	v_mov_b32_dpp v158, v122 quad_perm:[2,3,0,1] row_mask:0xf bank_mask:0xf bound_ctrl:1
	v_mov_b32_dpp v159, v123 quad_perm:[2,3,0,1] row_mask:0xf bank_mask:0xf bound_ctrl:1
	v_add_f32_e32 v122, v122, v158
	v_add_f32_e32 v123, v123, v159
	v_fmac_f32_e32 v164, v158, v155
	ds_write_b16 v196, v157 offset:176
	v_mov_b32_dpp v160, v122 row_half_mirror row_mask:0xf bank_mask:0xf bound_ctrl:1
; __device__ void phase_attn(const Params& p, char* smem) {
;     ...
;         if (kbase + 31 >= q0) { ATT_TILE(true) } else { ATT_TILE(false) }
	v_mov_b32_dpp v161, v123 row_half_mirror row_mask:0xf bank_mask:0xf bound_ctrl:1
	v_add_f32_e32 v122, v122, v160
	v_add_f32_e32 v123, v123, v161
	v_fmac_f32_e32 v164, v160, v180
	v_cmp_lt_u32_e64 s[8:9], v127, v129
	v_mov_b32_dpp v162, v122 row_ror:8 row_mask:0xf bank_mask:0xf bound_ctrl:1
	v_fmac_f32_e32 v164, v162, v181
	v_add_f32_e32 v124, v124, v164
	v_exp_f32_e32 v124, v124
	v_mov_b32_dpp v163, v123 row_ror:8 row_mask:0xf bank_mask:0xf bound_ctrl:1
	v_add_f32_e32 v122, v122, v162
	v_add_f32_e32 v123, v123, v163
	v_cmp_lt_u32_e64 s[10:11], v127, v150
	v_cvt_pk_bf16_f32 v124, v124, s0
	v_cndmask_b32_e32 v124, 0, v124, vcc
	ds_write_b16 v196, v124
	v_fma_f32 v124, v125, v153, 0
	v_fmac_f32_e32 v124, v159, v155
	v_fmac_f32_e32 v124, v161, v180
	v_fmac_f32_e32 v124, v163, v181
	v_sub_f32_e32 v125, v119, v133
	v_add_f32_e32 v133, v125, v124
	v_mul_f32_e32 v124, s24, v94
	v_mul_f32_e32 v125, s24, v95
	v_add_f32_e32 v118, v118, v122
	v_add_f32_e32 v119, v119, v123
	v_exp_f32_e64 v157, -|v124|
	v_exp_f32_e64 v158, -|v125|
	v_max_f32_e64 v124, -v124, 0
	v_max_f32_e64 v125, -v125, 0
	v_add_f32_e32 v122, 1.0, v157
	v_add_f32_e32 v123, 1.0, v158
	v_log_f32_e32 v122, v122
	v_log_f32_e32 v123, v123
	v_exp_f32_e32 v133, v133
	v_add_f32_e32 v122, v124, v122
	v_add_f32_e32 v123, v125, v123
	s_nop 0
	v_fma_f32 v124, -v94, s24, -v122
	v_fma_f32 v125, -v95, s24, -v123
	v_sub_f32_e32 v122, v116, v122
	v_sub_f32_e32 v123, v117, v123
	v_cndmask_b32_e64 v125, 0, v125, s[8:9]
	v_cndmask_b32_e64 v124, 0, v124, s[10:11]
	v_cvt_pk_bf16_f32 v133, v133, s0
	v_mov_b32_dpp v159, v125 quad_perm:[1,0,3,2] row_mask:0xf bank_mask:0xf bound_ctrl:1
	v_mov_b32_dpp v158, v124 quad_perm:[1,0,3,2] row_mask:0xf bank_mask:0xf bound_ctrl:1
	v_add_f32_e32 v124, v124, v158
	v_add_f32_e32 v125, v125, v159
	v_fma_f32 v157, v158, v153, 0
	v_cndmask_b32_e64 v133, v133, 0, s[6:7]
	v_mov_b32_dpp v160, v124 quad_perm:[2,3,0,1] row_mask:0xf bank_mask:0xf bound_ctrl:1
	v_mov_b32_dpp v161, v125 quad_perm:[2,3,0,1] row_mask:0xf bank_mask:0xf bound_ctrl:1
	v_add_f32_e32 v124, v124, v160
	v_add_f32_e32 v125, v125, v161
	v_fmac_f32_e32 v157, v160, v155
	ds_write_b16 v196, v133 offset:144
	v_mov_b32_dpp v162, v124 row_half_mirror row_mask:0xf bank_mask:0xf bound_ctrl:1
	v_mov_b32_dpp v163, v125 row_half_mirror row_mask:0xf bank_mask:0xf bound_ctrl:1
	v_add_f32_e32 v124, v124, v162
	v_add_f32_e32 v125, v125, v163
	v_fmac_f32_e32 v157, v162, v180
	v_cmp_lt_u32_e64 s[6:7], v126, v129
	v_mov_b32_dpp v164, v124 row_ror:8 row_mask:0xf bank_mask:0xf bound_ctrl:1
	v_fmac_f32_e32 v157, v164, v181
	v_add_f32_e32 v122, v122, v157
	v_exp_f32_e32 v122, v122
	v_mov_b32_dpp v165, v125 row_ror:8 row_mask:0xf bank_mask:0xf bound_ctrl:1
	v_add_f32_e32 v124, v124, v164
	v_add_f32_e32 v125, v125, v165
	v_cvt_pk_bf16_f32 v122, v122, s0
	v_cndmask_b32_e64 v122, 0, v122, s[10:11]
	ds_write_b16 v196, v122 offset:320
	v_fma_f32 v122, v159, v153, 0
	v_fmac_f32_e32 v122, v161, v155
	v_fmac_f32_e32 v122, v163, v180
	v_fmac_f32_e32 v122, v165, v181
	v_add_f32_e32 v122, v123, v122
	v_exp_f32_e32 v133, v122
	v_mul_f32_e32 v122, s24, v90
	v_mul_f32_e32 v123, s24, v91
	v_add_f32_e32 v124, v116, v124
	v_add_f32_e32 v125, v117, v125
	v_exp_f32_e64 v157, -|v122|
	v_exp_f32_e64 v159, -|v123|
	v_max_f32_e64 v122, -v122, 0
	v_max_f32_e64 v123, -v123, 0
	v_add_f32_e32 v157, 1.0, v157
	v_log_f32_e32 v158, v157
	v_add_f32_e32 v157, 1.0, v159
	v_log_f32_e32 v159, v157
	v_cvt_pk_bf16_f32 v133, v133, s0
	v_cndmask_b32_e64 v133, 0, v133, s[8:9]
	v_cmp_lt_u32_e64 s[8:9], v126, v150
	v_add_f32_e32 v122, v122, v158
	v_add_f32_e32 v123, v123, v159
	ds_write_b16 v196, v133 offset:464
	v_fma_f32 v158, -v90, s24, -v122
	v_fma_f32 v159, -v91, s24, -v123
	v_sub_f32_e32 v122, v124, v122
	v_sub_f32_e32 v123, v125, v123
	v_cndmask_b32_e64 v159, 0, v159, s[6:7]
	v_cndmask_b32_e64 v158, 0, v158, s[8:9]
	s_nop 0
	v_mov_b32_dpp v161, v159 quad_perm:[1,0,3,2] row_mask:0xf bank_mask:0xf bound_ctrl:1
	v_mov_b32_dpp v160, v158 quad_perm:[1,0,3,2] row_mask:0xf bank_mask:0xf bound_ctrl:1
	v_add_f32_e32 v158, v158, v160
	v_add_f32_e32 v159, v159, v161
	v_fma_f32 v157, v160, v153, 0
	s_nop 0
	v_mov_b32_dpp v162, v158 quad_perm:[2,3,0,1] row_mask:0xf bank_mask:0xf bound_ctrl:1
	v_mov_b32_dpp v163, v159 quad_perm:[2,3,0,1] row_mask:0xf bank_mask:0xf bound_ctrl:1
	v_add_f32_e32 v158, v158, v162
	v_add_f32_e32 v159, v159, v163
	v_fmac_f32_e32 v157, v162, v155
	s_nop 0
	v_mov_b32_dpp v164, v158 row_half_mirror row_mask:0xf bank_mask:0xf bound_ctrl:1
	v_mov_b32_dpp v165, v159 row_half_mirror row_mask:0xf bank_mask:0xf bound_ctrl:1
	v_add_f32_e32 v158, v158, v164
	v_add_f32_e32 v159, v159, v165
	v_fmac_f32_e32 v157, v164, v180
	s_nop 0
	v_mov_b32_dpp v166, v158 row_ror:8 row_mask:0xf bank_mask:0xf bound_ctrl:1
	v_fmac_f32_e32 v157, v166, v181
	v_add_f32_e32 v122, v122, v157
	v_exp_f32_e32 v122, v122
	v_mov_b32_dpp v167, v159 row_ror:8 row_mask:0xf bank_mask:0xf bound_ctrl:1
	v_add_f32_e32 v158, v158, v166
	v_add_f32_e32 v159, v159, v167
	v_cvt_pk_bf16_f32 v122, v122, s0
	v_cndmask_b32_e64 v122, 0, v122, s[8:9]
	ds_write_b16 v196, v122 offset:288
	v_fma_f32 v122, v161, v153, 0
	v_mul_f32_e32 v160, s24, v84
	v_mul_f32_e32 v161, s24, v85
	v_fmac_f32_e32 v122, v163, v155
	v_exp_f32_e64 v133, -|v160|
	v_exp_f32_e64 v162, -|v161|
	v_fmac_f32_e32 v122, v165, v180
	v_fmac_f32_e32 v122, v167, v181
	v_add_f32_e32 v122, v123, v122
	v_exp_f32_e32 v157, v122
	v_add_f32_e32 v122, v124, v158
	v_add_f32_e32 v123, v125, v159
	v_add_f32_e32 v124, 1.0, v133
	v_add_f32_e32 v125, 1.0, v162
	v_log_f32_e32 v124, v124
	v_log_f32_e32 v125, v125
	v_max_f32_e64 v158, -v160, 0
	v_max_f32_e64 v159, -v161, 0
; __device__ void phase_attn(const Params& p, char* smem) {
;     ...
;         if (kbase + 31 >= q0) { ATT_TILE(true) } else { ATT_TILE(false) }
	v_cmp_lt_u32_e64 s[8:9], v127, v131
	v_add_f32_e32 v124, v158, v124
	v_add_f32_e32 v125, v159, v125
	v_cvt_pk_bf16_f32 v133, v157, s0
	v_sub_f32_e32 v158, v114, v124
	v_sub_f32_e32 v159, v115, v125
	v_fma_f32 v124, -v84, s24, -v124
	v_fma_f32 v125, -v85, s24, -v125
	v_cndmask_b32_e64 v133, 0, v133, s[6:7]
	v_cndmask_b32_e64 v125, 0, v125, s[8:9]
	v_cndmask_b32_e32 v124, 0, v124, vcc
	ds_write_b16 v196, v133 offset:432
	v_mov_b32_dpp v161, v125 quad_perm:[1,0,3,2] row_mask:0xf bank_mask:0xf bound_ctrl:1
	v_mov_b32_dpp v160, v124 quad_perm:[1,0,3,2] row_mask:0xf bank_mask:0xf bound_ctrl:1
	v_add_f32_e32 v124, v124, v160
	v_add_f32_e32 v125, v125, v161
	v_fma_f32 v157, v161, v153, 0
	v_cmp_lt_u32_e64 s[6:7], v126, v152
	v_mov_b32_dpp v163, v125 quad_perm:[2,3,0,1] row_mask:0xf bank_mask:0xf bound_ctrl:1
	v_mov_b32_dpp v162, v124 quad_perm:[2,3,0,1] row_mask:0xf bank_mask:0xf bound_ctrl:1
	v_add_f32_e32 v124, v124, v162
	v_add_f32_e32 v125, v125, v163
	v_fmac_f32_e32 v157, v163, v155
	s_nop 0
	v_mov_b32_dpp v165, v125 row_half_mirror row_mask:0xf bank_mask:0xf bound_ctrl:1
	v_mov_b32_dpp v164, v124 row_half_mirror row_mask:0xf bank_mask:0xf bound_ctrl:1
	v_add_f32_e32 v124, v124, v164
	v_add_f32_e32 v125, v125, v165
	v_fmac_f32_e32 v157, v165, v180
	s_nop 0
	v_mov_b32_dpp v167, v125 row_ror:8 row_mask:0xf bank_mask:0xf bound_ctrl:1
	v_fmac_f32_e32 v157, v167, v181
	v_add_f32_e32 v157, v159, v157
	v_exp_f32_e32 v157, v157
	v_mov_b32_dpp v166, v124 row_ror:8 row_mask:0xf bank_mask:0xf bound_ctrl:1
	v_add_f32_e32 v124, v124, v166
	v_add_f32_e32 v125, v125, v167
	v_cvt_pk_bf16_f32 v133, v157, s0
	v_cndmask_b32_e64 v133, 0, v133, s[8:9]
	ds_write_b16 v196, v133 offset:2480
	v_fma_f32 v133, v160, v153, 0
	v_fmac_f32_e32 v133, v162, v155
	v_fmac_f32_e32 v133, v164, v180
	v_fmac_f32_e32 v133, v166, v181
	v_add_f32_e32 v133, v158, v133
	v_mul_f32_e32 v158, s24, v80
	v_mul_f32_e32 v159, s24, v81
	v_exp_f32_e32 v133, v133
	v_exp_f32_e64 v157, -|v158|
	v_exp_f32_e64 v161, -|v159|
	v_max_f32_e64 v158, -v158, 0
	v_max_f32_e64 v159, -v159, 0
	v_add_f32_e32 v157, 1.0, v157
	v_log_f32_e32 v160, v157
	v_add_f32_e32 v157, 1.0, v161
	v_log_f32_e32 v161, v157
	v_cvt_pk_bf16_f32 v133, v133, s0
	v_cndmask_b32_e32 v133, 0, v133, vcc
	v_cmp_lt_u32_e32 vcc, v126, v131
	v_add_f32_e32 v158, v158, v160
	v_add_f32_e32 v159, v159, v161
	v_add_f32_e32 v124, v114, v124
	v_add_f32_e32 v125, v115, v125
	v_fma_f32 v160, -v80, s24, -v158
	v_fma_f32 v161, -v81, s24, -v159
	v_sub_f32_e32 v158, v124, v158
	v_sub_f32_e32 v159, v125, v159
	v_cndmask_b32_e32 v161, 0, v161, vcc
	v_cndmask_b32_e64 v160, 0, v160, s[6:7]
	ds_write_b16 v196, v133 offset:2336
	v_mov_b32_dpp v163, v161 quad_perm:[1,0,3,2] row_mask:0xf bank_mask:0xf bound_ctrl:1
	v_mov_b32_dpp v162, v160 quad_perm:[1,0,3,2] row_mask:0xf bank_mask:0xf bound_ctrl:1
	v_add_f32_e32 v160, v160, v162
	v_add_f32_e32 v161, v161, v163
	v_fma_f32 v157, v162, v153, 0
	v_cmp_lt_u32_e64 s[8:9], v127, v154
	v_mov_b32_dpp v164, v160 quad_perm:[2,3,0,1] row_mask:0xf bank_mask:0xf bound_ctrl:1
	v_mov_b32_dpp v165, v161 quad_perm:[2,3,0,1] row_mask:0xf bank_mask:0xf bound_ctrl:1
	v_add_f32_e32 v160, v160, v164
	v_add_f32_e32 v161, v161, v165
	v_fmac_f32_e32 v157, v164, v155
	s_nop 0
	v_mov_b32_dpp v166, v160 row_half_mirror row_mask:0xf bank_mask:0xf bound_ctrl:1
	v_mov_b32_dpp v167, v161 row_half_mirror row_mask:0xf bank_mask:0xf bound_ctrl:1
	v_add_f32_e32 v160, v160, v166
	v_add_f32_e32 v161, v161, v167
	v_fmac_f32_e32 v157, v166, v180
	s_nop 0
	v_mov_b32_dpp v168, v160 row_ror:8 row_mask:0xf bank_mask:0xf bound_ctrl:1
	v_fmac_f32_e32 v157, v168, v181
	v_add_f32_e32 v157, v158, v157
	v_exp_f32_e32 v157, v157
	v_mov_b32_dpp v169, v161 row_ror:8 row_mask:0xf bank_mask:0xf bound_ctrl:1
	v_add_f32_e32 v160, v160, v168
	v_add_f32_e32 v161, v161, v169
	v_cvt_pk_bf16_f32 v133, v157, s0
	v_cndmask_b32_e64 v133, 0, v133, s[6:7]
	ds_write_b16 v196, v133 offset:2304
	v_fma_f32 v133, v163, v153, 0
	v_fmac_f32_e32 v133, v165, v155
	v_fmac_f32_e32 v133, v167, v180
	v_fmac_f32_e32 v133, v169, v181
	v_add_f32_e32 v133, v159, v133
	v_mul_f32_e32 v158, s24, v86
	v_mul_f32_e32 v159, s24, v87
	v_add_f32_e32 v124, v124, v160
	v_add_f32_e32 v125, v125, v161
	v_exp_f32_e64 v157, -|v158|
	v_exp_f32_e64 v162, -|v159|
	v_max_f32_e64 v158, -v158, 0
	v_max_f32_e64 v159, -v159, 0
	v_add_f32_e32 v157, 1.0, v157
	v_log_f32_e32 v160, v157
	v_add_f32_e32 v157, 1.0, v162
	v_log_f32_e32 v161, v157
	v_cmp_lt_u32_e64 s[6:7], v127, v149
	v_exp_f32_e32 v133, v133
	v_add_f32_e32 v158, v158, v160
	v_add_f32_e32 v159, v159, v161
	s_nop 0
	v_fma_f32 v160, -v86, s24, -v158
	v_fma_f32 v161, -v87, s24, -v159
	v_sub_f32_e32 v158, v112, v158
	v_sub_f32_e32 v159, v113, v159
	v_cndmask_b32_e64 v161, 0, v161, s[6:7]
	v_cndmask_b32_e64 v160, 0, v160, s[8:9]
	v_cvt_pk_bf16_f32 v133, v133, s0
	v_mov_b32_dpp v163, v161 quad_perm:[1,0,3,2] row_mask:0xf bank_mask:0xf bound_ctrl:1
	v_mov_b32_dpp v162, v160 quad_perm:[1,0,3,2] row_mask:0xf bank_mask:0xf bound_ctrl:1
	v_add_f32_e32 v160, v160, v162
	v_add_f32_e32 v161, v161, v163
	v_fma_f32 v127, v162, v153, 0
	v_cndmask_b32_e32 v133, 0, v133, vcc
	v_mov_b32_dpp v164, v160 quad_perm:[2,3,0,1] row_mask:0xf bank_mask:0xf bound_ctrl:1
	v_mov_b32_dpp v165, v161 quad_perm:[2,3,0,1] row_mask:0xf bank_mask:0xf bound_ctrl:1
	v_add_f32_e32 v160, v160, v164
	v_add_f32_e32 v161, v161, v165
	v_fmac_f32_e32 v127, v164, v155
	ds_write_b16 v196, v133 offset:2448
	v_mov_b32_dpp v166, v160 row_half_mirror row_mask:0xf bank_mask:0xf bound_ctrl:1
	v_mov_b32_dpp v167, v161 row_half_mirror row_mask:0xf bank_mask:0xf bound_ctrl:1
	v_add_f32_e32 v160, v160, v166
; __device__ void phase_attn(const Params& p, char* smem) {
;     ...
;         if (kbase + 31 >= q0) { ATT_TILE(true) } else { ATT_TILE(false) }
	v_add_f32_e32 v161, v161, v167
	v_fmac_f32_e32 v127, v166, v180
	v_cmp_lt_u32_e32 vcc, v126, v149
	v_mov_b32_dpp v168, v160 row_ror:8 row_mask:0xf bank_mask:0xf bound_ctrl:1
	v_fmac_f32_e32 v127, v168, v181
	v_add_f32_e32 v127, v158, v127
	v_exp_f32_e32 v127, v127
	v_mov_b32_dpp v169, v161 row_ror:8 row_mask:0xf bank_mask:0xf bound_ctrl:1
	v_add_f32_e32 v160, v160, v168
	v_add_f32_e32 v161, v161, v169
	v_cvt_pk_bf16_f32 v127, v127, s0
	v_cndmask_b32_e64 v127, 0, v127, s[8:9]
	ds_write_b16 v196, v127 offset:2624
	v_fma_f32 v127, v163, v153, 0
	v_fmac_f32_e32 v127, v165, v155
	v_fmac_f32_e32 v127, v167, v180
	v_fmac_f32_e32 v127, v169, v181
	v_add_f32_e32 v127, v159, v127
	v_mul_f32_e32 v158, s24, v82
	v_mul_f32_e32 v159, s24, v83
	v_exp_f32_e32 v127, v127
	v_exp_f32_e64 v133, -|v158|
	v_exp_f32_e64 v157, -|v159|
	v_max_f32_e64 v158, -v158, 0
	v_max_f32_e64 v159, -v159, 0
	v_add_f32_e32 v133, 1.0, v133
	v_log_f32_e32 v162, v133
	v_add_f32_e32 v133, 1.0, v157
	v_log_f32_e32 v163, v133
	v_cvt_pk_bf16_f32 v127, v127, s0
	v_cndmask_b32_e64 v133, 0, v127, s[6:7]
	v_cmp_lt_u32_e64 s[6:7], v126, v154
	v_add_f32_e32 v158, v158, v162
	v_add_f32_e32 v159, v159, v163
	v_add_f32_e32 v160, v112, v160
	v_add_f32_e32 v161, v113, v161
	v_fma_f32 v162, -v82, s24, -v158
	v_fma_f32 v163, -v83, s24, -v159
	v_sub_f32_e32 v158, v160, v158
	v_sub_f32_e32 v159, v161, v159
	v_cndmask_b32_e32 v127, 0, v163, vcc
	v_cndmask_b32_e64 v126, 0, v162, s[6:7]
	ds_write_b16 v196, v133 offset:2768
	v_mov_b32_dpp v163, v127 quad_perm:[1,0,3,2] row_mask:0xf bank_mask:0xf bound_ctrl:1
	v_mov_b32_dpp v162, v126 quad_perm:[1,0,3,2] row_mask:0xf bank_mask:0xf bound_ctrl:1
	v_add_f32_e32 v126, v126, v162
	v_add_f32_e32 v127, v127, v163
	v_fma_f32 v157, v162, v153, 0
	s_nop 0
	v_mov_b32_dpp v164, v126 quad_perm:[2,3,0,1] row_mask:0xf bank_mask:0xf bound_ctrl:1
	v_mov_b32_dpp v165, v127 quad_perm:[2,3,0,1] row_mask:0xf bank_mask:0xf bound_ctrl:1
	v_add_f32_e32 v126, v126, v164
	v_add_f32_e32 v127, v127, v165
	v_fmac_f32_e32 v157, v164, v155
	s_nop 0
	v_mov_b32_dpp v166, v126 row_half_mirror row_mask:0xf bank_mask:0xf bound_ctrl:1
	v_mov_b32_dpp v167, v127 row_half_mirror row_mask:0xf bank_mask:0xf bound_ctrl:1
	v_add_f32_e32 v126, v126, v166
	v_add_f32_e32 v127, v127, v167
	v_fmac_f32_e32 v157, v166, v180
	s_nop 0
	v_mov_b32_dpp v168, v126 row_ror:8 row_mask:0xf bank_mask:0xf bound_ctrl:1
	v_fmac_f32_e32 v157, v168, v181
	v_add_f32_e32 v157, v158, v157
	v_exp_f32_e32 v157, v157
	v_mov_b32_dpp v169, v127 row_ror:8 row_mask:0xf bank_mask:0xf bound_ctrl:1
	v_add_f32_e32 v126, v126, v168
	v_add_f32_e32 v127, v127, v169
	v_cvt_pk_bf16_f32 v133, v157, s0
	v_fma_f32 v157, v163, v153, 0
	v_fmac_f32_e32 v157, v165, v155
	v_fmac_f32_e32 v157, v167, v180
	v_fmac_f32_e32 v157, v169, v181
	v_add_f32_e32 v157, v159, v157
	v_exp_f32_e32 v157, v157
	v_cndmask_b32_e64 v133, 0, v133, s[6:7]
	ds_write_b16 v196, v133 offset:2592
	v_add_f32_e32 v126, v160, v126
	v_add_f32_e32 v127, v161, v127
	v_cvt_pk_bf16_f32 v133, v157, s0
	v_cndmask_b32_e32 v133, 0, v133, vcc
	s_mov_b64 s[6:7], 0
.LBB0_227:
	s_andn2_b64 vcc, exec, s[6:7]
	s_cbranch_vccnz .LBB0_224
	s_nop 0
	v_mul_f32_e32 v118, s24, v92
	v_mul_f32_e32 v119, s24, v93
	s_nop 0
	v_exp_f32_e64 v122, -|v118|
	v_exp_f32_e64 v123, -|v119|
	v_max_f32_e64 v118, -v118, 0
	v_max_f32_e64 v119, -v119, 0
	v_add_f32_e32 v122, 1.0, v122
	v_add_f32_e32 v123, 1.0, v123
	v_log_f32_e32 v122, v122
	v_log_f32_e32 v123, v123
	s_nop 0
	v_add_f32_e32 v118, v118, v122
	v_add_f32_e32 v119, v119, v123
	s_nop 0
	v_fma_f32 v92, -v92, s24, -v118
	v_fma_f32 v93, -v93, s24, -v119
	v_sub_f32_e32 v118, v120, v118
	v_sub_f32_e32 v119, v121, v119
	s_nop 0
	v_mov_b32_dpp v122, v92 quad_perm:[1,0,3,2] row_mask:0xf bank_mask:0xf bound_ctrl:1
	v_mov_b32_dpp v123, v93 quad_perm:[1,0,3,2] row_mask:0xf bank_mask:0xf bound_ctrl:1
	v_add_f32_e32 v92, v92, v122
	v_add_f32_e32 v93, v93, v123
	v_fma_f32 v133, v122, v153, 0
	s_nop 0
	v_mov_b32_dpp v124, v92 quad_perm:[2,3,0,1] row_mask:0xf bank_mask:0xf bound_ctrl:1
	v_mov_b32_dpp v125, v93 quad_perm:[2,3,0,1] row_mask:0xf bank_mask:0xf bound_ctrl:1
	v_add_f32_e32 v92, v92, v124
	v_add_f32_e32 v93, v93, v125
	v_fmac_f32_e32 v133, v124, v155
	s_nop 0
	v_mov_b32_dpp v126, v92 row_half_mirror row_mask:0xf bank_mask:0xf bound_ctrl:1
	v_mov_b32_dpp v127, v93 row_half_mirror row_mask:0xf bank_mask:0xf bound_ctrl:1
	v_add_f32_e32 v92, v92, v126
	v_add_f32_e32 v93, v93, v127
	v_fmac_f32_e32 v133, v126, v180
	s_nop 0
	v_mov_b32_dpp v158, v92 row_ror:8 row_mask:0xf bank_mask:0xf bound_ctrl:1
	v_fmac_f32_e32 v133, v158, v181
	v_add_f32_e32 v118, v118, v133
	v_exp_f32_e32 v118, v118
	v_mov_b32_dpp v159, v93 row_ror:8 row_mask:0xf bank_mask:0xf bound_ctrl:1
	v_add_f32_e32 v92, v92, v158
	v_add_f32_e32 v93, v93, v159
	v_cvt_pk_bf16_f32 v118, v118, s0
	ds_write_b16 v196, v118 offset:32
	v_fma_f32 v118, v123, v153, 0
	v_fmac_f32_e32 v118, v125, v155
	v_fmac_f32_e32 v118, v127, v180
	v_fmac_f32_e32 v118, v159, v181
	v_add_f32_e32 v122, v119, v118
	v_mul_f32_e32 v118, s24, v88
	v_mul_f32_e32 v119, s24, v89
	v_add_f32_e32 v92, v120, v92
	v_add_f32_e32 v93, v121, v93
	v_exp_f32_e64 v123, -|v118|
	v_exp_f32_e64 v124, -|v119|
	v_max_f32_e64 v118, -v118, 0
	v_max_f32_e64 v119, -v119, 0
	v_add_f32_e32 v120, 1.0, v123
	v_add_f32_e32 v121, 1.0, v124
	v_log_f32_e32 v120, v120
	v_log_f32_e32 v121, v121
	v_exp_f32_e32 v122, v122
	v_add_f32_e32 v118, v118, v120
	v_add_f32_e32 v119, v119, v121
	s_nop 0
	v_fma_f32 v88, -v88, s24, -v118
	v_fma_f32 v89, -v89, s24, -v119
	v_cvt_pk_bf16_f32 v127, v122, s0
	v_sub_f32_e32 v118, v92, v118
	v_sub_f32_e32 v119, v93, v119
; __device__ void phase_attn(const Params& p, char* smem) {
;     ...
;         if (kbase + 31 >= q0) { ATT_TILE(true) } else { ATT_TILE(false) }
	v_mov_b32_dpp v120, v88 quad_perm:[1,0,3,2] row_mask:0xf bank_mask:0xf bound_ctrl:1
	v_mov_b32_dpp v121, v89 quad_perm:[1,0,3,2] row_mask:0xf bank_mask:0xf bound_ctrl:1
	v_add_f32_e32 v88, v88, v120
	v_add_f32_e32 v89, v89, v121
	v_fma_f32 v133, v120, v153, 0
	ds_write_b16 v196, v127 offset:176
	v_mov_b32_dpp v122, v88 quad_perm:[2,3,0,1] row_mask:0xf bank_mask:0xf bound_ctrl:1
	v_mov_b32_dpp v123, v89 quad_perm:[2,3,0,1] row_mask:0xf bank_mask:0xf bound_ctrl:1
	v_add_f32_e32 v88, v88, v122
	v_add_f32_e32 v89, v89, v123
	v_fmac_f32_e32 v133, v122, v155
	s_nop 0
	v_mov_b32_dpp v124, v88 row_half_mirror row_mask:0xf bank_mask:0xf bound_ctrl:1
	v_mov_b32_dpp v125, v89 row_half_mirror row_mask:0xf bank_mask:0xf bound_ctrl:1
	v_add_f32_e32 v88, v88, v124
	v_add_f32_e32 v89, v89, v125
	v_fmac_f32_e32 v133, v124, v180
	s_nop 0
	v_mov_b32_dpp v126, v88 row_ror:8 row_mask:0xf bank_mask:0xf bound_ctrl:1
	v_fmac_f32_e32 v133, v126, v181
	v_add_f32_e32 v118, v118, v133
	v_exp_f32_e32 v118, v118
	v_mov_b32_dpp v127, v89 row_ror:8 row_mask:0xf bank_mask:0xf bound_ctrl:1
	v_add_f32_e32 v88, v88, v126
	v_add_f32_e32 v89, v89, v127
	v_cvt_pk_bf16_f32 v118, v118, s0
	ds_write_b16 v196, v118
	v_fma_f32 v118, v121, v153, 0
	v_fmac_f32_e32 v118, v123, v155
	v_fmac_f32_e32 v118, v125, v180
	v_mul_f32_e32 v120, s24, v94
	v_mul_f32_e32 v121, s24, v95
	v_fmac_f32_e32 v118, v127, v181
	v_exp_f32_e64 v122, -|v120|
	v_add_f32_e32 v118, v119, v118
	v_exp_f32_e64 v119, -|v121|
	v_exp_f32_e32 v125, v118
	v_add_f32_e32 v118, 1.0, v122
	v_log_f32_e32 v122, v118
	v_add_f32_e32 v118, 1.0, v119
	v_log_f32_e32 v123, v118
	v_add_f32_e32 v118, v92, v88
	v_add_f32_e32 v119, v93, v89
	v_max_f32_e64 v88, -v120, 0
	v_max_f32_e64 v89, -v121, 0
	v_add_f32_e32 v88, v88, v122
	v_add_f32_e32 v89, v89, v123
	s_nop 0
	v_fma_f32 v92, -v94, s24, -v88
	v_fma_f32 v93, -v95, s24, -v89
	v_sub_f32_e32 v88, v116, v88
	v_sub_f32_e32 v89, v117, v89
	s_nop 0
	v_mov_b32_dpp v94, v92 quad_perm:[1,0,3,2] row_mask:0xf bank_mask:0xf bound_ctrl:1
	v_mov_b32_dpp v95, v93 quad_perm:[1,0,3,2] row_mask:0xf bank_mask:0xf bound_ctrl:1
	v_add_f32_e32 v92, v92, v94
	v_add_f32_e32 v93, v93, v95
	v_fma_f32 v126, v94, v153, 0
	v_cvt_pk_bf16_f32 v94, v125, s0
	v_mov_b32_dpp v120, v92 quad_perm:[2,3,0,1] row_mask:0xf bank_mask:0xf bound_ctrl:1
	v_mov_b32_dpp v121, v93 quad_perm:[2,3,0,1] row_mask:0xf bank_mask:0xf bound_ctrl:1
	v_add_f32_e32 v92, v92, v120
	v_add_f32_e32 v93, v93, v121
	v_fmac_f32_e32 v126, v120, v155
	ds_write_b16 v196, v94 offset:144
	v_mov_b32_dpp v122, v92 row_half_mirror row_mask:0xf bank_mask:0xf bound_ctrl:1
	v_mov_b32_dpp v123, v93 row_half_mirror row_mask:0xf bank_mask:0xf bound_ctrl:1
	v_add_f32_e32 v92, v92, v122
	v_add_f32_e32 v93, v93, v123
	v_fmac_f32_e32 v126, v122, v180
	s_nop 0
	v_mov_b32_dpp v124, v92 row_ror:8 row_mask:0xf bank_mask:0xf bound_ctrl:1
	v_fmac_f32_e32 v126, v124, v181
	v_add_f32_e32 v88, v88, v126
	v_exp_f32_e32 v88, v88
	v_mov_b32_dpp v125, v93 row_ror:8 row_mask:0xf bank_mask:0xf bound_ctrl:1
	v_add_f32_e32 v92, v92, v124
	v_add_f32_e32 v93, v93, v125
	v_cvt_pk_bf16_f32 v88, v88, s0
	ds_write_b16 v196, v88 offset:320
	v_fma_f32 v88, v95, v153, 0
	v_fmac_f32_e32 v88, v121, v155
	v_fmac_f32_e32 v88, v123, v180
	v_fmac_f32_e32 v88, v125, v181
	v_add_f32_e32 v94, v89, v88
	v_mul_f32_e32 v88, s24, v90
	v_mul_f32_e32 v89, s24, v91
	v_exp_f32_e32 v120, v94
	v_exp_f32_e64 v95, -|v88|
	v_exp_f32_e64 v121, -|v89|
	v_max_f32_e64 v88, -v88, 0
	v_max_f32_e64 v89, -v89, 0
	v_add_f32_e32 v94, 1.0, v95
	v_add_f32_e32 v95, 1.0, v121
	v_log_f32_e32 v94, v94
	v_log_f32_e32 v95, v95
	v_add_f32_e32 v92, v116, v92
	v_add_f32_e32 v93, v117, v93
	v_cvt_pk_bf16_f32 v123, v120, s0
	ds_write_b16 v196, v123 offset:464
	v_add_f32_e32 v88, v88, v94
	v_add_f32_e32 v89, v89, v95
	s_nop 0
	v_fma_f32 v90, -v90, s24, -v88
	v_fma_f32 v91, -v91, s24, -v89
	v_sub_f32_e32 v88, v92, v88
	v_sub_f32_e32 v89, v93, v89
	s_nop 0
	v_mov_b32_dpp v94, v90 quad_perm:[1,0,3,2] row_mask:0xf bank_mask:0xf bound_ctrl:1
	v_mov_b32_dpp v95, v91 quad_perm:[1,0,3,2] row_mask:0xf bank_mask:0xf bound_ctrl:1
	v_add_f32_e32 v90, v90, v94
	v_add_f32_e32 v91, v91, v95
	v_fma_f32 v124, v94, v153, 0
	s_nop 0
	v_mov_b32_dpp v116, v90 quad_perm:[2,3,0,1] row_mask:0xf bank_mask:0xf bound_ctrl:1
	v_mov_b32_dpp v117, v91 quad_perm:[2,3,0,1] row_mask:0xf bank_mask:0xf bound_ctrl:1
	v_add_f32_e32 v90, v90, v116
	v_add_f32_e32 v91, v91, v117
	v_fmac_f32_e32 v124, v116, v155
	s_nop 0
	v_mov_b32_dpp v120, v90 row_half_mirror row_mask:0xf bank_mask:0xf bound_ctrl:1
	v_mov_b32_dpp v121, v91 row_half_mirror row_mask:0xf bank_mask:0xf bound_ctrl:1
	v_add_f32_e32 v90, v90, v120
	v_add_f32_e32 v91, v91, v121
	v_fmac_f32_e32 v124, v120, v180
	s_nop 0
	v_mov_b32_dpp v122, v90 row_ror:8 row_mask:0xf bank_mask:0xf bound_ctrl:1
	v_fmac_f32_e32 v124, v122, v181
	v_add_f32_e32 v88, v88, v124
	v_exp_f32_e32 v88, v88
	v_mov_b32_dpp v123, v91 row_ror:8 row_mask:0xf bank_mask:0xf bound_ctrl:1
	v_add_f32_e32 v90, v90, v122
	v_add_f32_e32 v91, v91, v123
	v_cvt_pk_bf16_f32 v88, v88, s0
	ds_write_b16 v196, v88 offset:288
	v_fma_f32 v88, v95, v153, 0
	v_fmac_f32_e32 v88, v117, v155
	v_fmac_f32_e32 v88, v121, v180
	v_fmac_f32_e32 v88, v123, v181
	v_mul_f32_e32 v94, s24, v84
	v_mul_f32_e32 v95, s24, v85
	v_add_f32_e32 v88, v89, v88
	v_exp_f32_e64 v116, -|v94|
	v_exp_f32_e64 v89, -|v95|
	v_exp_f32_e32 v117, v88
	v_add_f32_e32 v122, v92, v90
	v_add_f32_e32 v123, v93, v91
	v_add_f32_e32 v88, 1.0, v116
	v_add_f32_e32 v89, 1.0, v89
	v_log_f32_e32 v88, v88
	v_log_f32_e32 v89, v89
	v_max_f32_e64 v90, -v94, 0
	v_max_f32_e64 v91, -v95, 0
	v_add_f32_e32 v88, v90, v88
; __device__ void phase_attn(const Params& p, char* smem) {
;     ...
;         if (kbase + 31 >= q0) { ATT_TILE(true) } else { ATT_TILE(false) }
	v_add_f32_e32 v89, v91, v89
	s_nop 0
	v_fma_f32 v84, -v84, s24, -v88
	v_fma_f32 v85, -v85, s24, -v89
	v_sub_f32_e32 v88, v114, v88
	v_sub_f32_e32 v89, v115, v89
	s_nop 0
	v_mov_b32_dpp v90, v84 quad_perm:[1,0,3,2] row_mask:0xf bank_mask:0xf bound_ctrl:1
	v_mov_b32_dpp v91, v85 quad_perm:[1,0,3,2] row_mask:0xf bank_mask:0xf bound_ctrl:1
	v_add_f32_e32 v84, v84, v90
	v_add_f32_e32 v85, v85, v91
	v_fma_f32 v120, v90, v153, 0
	v_cvt_pk_bf16_f32 v90, v117, s0
	v_mov_b32_dpp v92, v84 quad_perm:[2,3,0,1] row_mask:0xf bank_mask:0xf bound_ctrl:1
	v_mov_b32_dpp v93, v85 quad_perm:[2,3,0,1] row_mask:0xf bank_mask:0xf bound_ctrl:1
	v_add_f32_e32 v84, v84, v92
	v_add_f32_e32 v85, v85, v93
	v_fmac_f32_e32 v120, v92, v155
	ds_write_b16 v196, v90 offset:432
	v_mov_b32_dpp v94, v84 row_half_mirror row_mask:0xf bank_mask:0xf bound_ctrl:1
	v_mov_b32_dpp v95, v85 row_half_mirror row_mask:0xf bank_mask:0xf bound_ctrl:1
	v_add_f32_e32 v84, v84, v94
	v_add_f32_e32 v85, v85, v95
	v_fmac_f32_e32 v120, v94, v180
	s_nop 0
	v_mov_b32_dpp v116, v84 row_ror:8 row_mask:0xf bank_mask:0xf bound_ctrl:1
	v_fmac_f32_e32 v120, v116, v181
	v_add_f32_e32 v88, v88, v120
	v_exp_f32_e32 v88, v88
	v_mov_b32_dpp v117, v85 row_ror:8 row_mask:0xf bank_mask:0xf bound_ctrl:1
	v_add_f32_e32 v84, v84, v116
	v_add_f32_e32 v85, v85, v117
	v_cvt_pk_bf16_f32 v88, v88, s0
	ds_write_b16 v196, v88 offset:2336
	v_fma_f32 v88, v91, v153, 0
	v_fmac_f32_e32 v88, v93, v155
	v_fmac_f32_e32 v88, v95, v180
	v_fmac_f32_e32 v88, v117, v181
	v_add_f32_e32 v90, v89, v88
	v_mul_f32_e32 v88, s24, v80
	v_mul_f32_e32 v89, s24, v81
	v_exp_f32_e32 v92, v90
	v_exp_f32_e64 v91, -|v88|
	v_exp_f32_e64 v93, -|v89|
	v_max_f32_e64 v88, -v88, 0
	v_max_f32_e64 v89, -v89, 0
	v_add_f32_e32 v90, 1.0, v91
	v_add_f32_e32 v91, 1.0, v93
	v_log_f32_e32 v90, v90
	v_log_f32_e32 v91, v91
	v_add_f32_e32 v84, v114, v84
	v_add_f32_e32 v85, v115, v85
	v_cvt_pk_bf16_f32 v115, v92, s0
	ds_write_b16 v196, v115 offset:2480
	v_add_f32_e32 v88, v88, v90
	v_add_f32_e32 v89, v89, v91
	s_nop 0
	v_fma_f32 v80, -v80, s24, -v88
	v_fma_f32 v81, -v81, s24, -v89
	v_sub_f32_e32 v88, v84, v88
	v_sub_f32_e32 v89, v85, v89
	s_nop 0
	v_mov_b32_dpp v90, v80 quad_perm:[1,0,3,2] row_mask:0xf bank_mask:0xf bound_ctrl:1
	v_mov_b32_dpp v91, v81 quad_perm:[1,0,3,2] row_mask:0xf bank_mask:0xf bound_ctrl:1
	v_add_f32_e32 v80, v80, v90
	v_add_f32_e32 v81, v81, v91
	v_fma_f32 v116, v90, v153, 0
	s_nop 0
	v_mov_b32_dpp v92, v80 quad_perm:[2,3,0,1] row_mask:0xf bank_mask:0xf bound_ctrl:1
	v_mov_b32_dpp v93, v81 quad_perm:[2,3,0,1] row_mask:0xf bank_mask:0xf bound_ctrl:1
	v_add_f32_e32 v80, v80, v92
	v_add_f32_e32 v81, v81, v93
	v_fmac_f32_e32 v116, v92, v155
	s_nop 0
	v_mov_b32_dpp v94, v80 row_half_mirror row_mask:0xf bank_mask:0xf bound_ctrl:1
	v_mov_b32_dpp v95, v81 row_half_mirror row_mask:0xf bank_mask:0xf bound_ctrl:1
	v_add_f32_e32 v80, v80, v94
	v_add_f32_e32 v81, v81, v95
	v_fmac_f32_e32 v116, v94, v180
	s_nop 0
	v_mov_b32_dpp v114, v80 row_ror:8 row_mask:0xf bank_mask:0xf bound_ctrl:1
	v_fmac_f32_e32 v116, v114, v181
	v_add_f32_e32 v88, v88, v116
	v_exp_f32_e32 v88, v88
	v_mov_b32_dpp v115, v81 row_ror:8 row_mask:0xf bank_mask:0xf bound_ctrl:1
	v_add_f32_e32 v80, v80, v114
	v_add_f32_e32 v81, v81, v115
	v_cvt_pk_bf16_f32 v88, v88, s0
	ds_write_b16 v196, v88 offset:2304
	v_fma_f32 v88, v91, v153, 0
	v_fmac_f32_e32 v88, v93, v155
	v_fmac_f32_e32 v88, v95, v180
	v_fmac_f32_e32 v88, v115, v181
	v_mul_f32_e32 v90, s24, v86
	v_mul_f32_e32 v91, s24, v87
	v_add_f32_e32 v88, v89, v88
	v_exp_f32_e64 v92, -|v90|
	v_exp_f32_e64 v89, -|v91|
	v_exp_f32_e32 v93, v88
	v_add_f32_e32 v124, v84, v80
	v_add_f32_e32 v125, v85, v81
	v_add_f32_e32 v88, 1.0, v92
; __device__ void phase_attn(const Params& p, char* smem) {
;     ...
;         if (kbase + 31 >= q0) { ATT_TILE(true) } else { ATT_TILE(false) }
	v_add_f32_e32 v89, 1.0, v89
	v_log_f32_e32 v88, v88
	v_log_f32_e32 v89, v89
	v_max_f32_e64 v80, -v90, 0
	v_max_f32_e64 v81, -v91, 0
	v_add_f32_e32 v80, v80, v88
	v_add_f32_e32 v81, v81, v89
	s_nop 0
	v_fma_f32 v84, -v86, s24, -v80
	v_fma_f32 v85, -v87, s24, -v81
	v_sub_f32_e32 v80, v112, v80
	v_sub_f32_e32 v81, v113, v81
	s_nop 0
	v_mov_b32_dpp v86, v84 quad_perm:[1,0,3,2] row_mask:0xf bank_mask:0xf bound_ctrl:1
	v_mov_b32_dpp v87, v85 quad_perm:[1,0,3,2] row_mask:0xf bank_mask:0xf bound_ctrl:1
	v_add_f32_e32 v84, v84, v86
	v_add_f32_e32 v85, v85, v87
	v_fma_f32 v94, v86, v153, 0
	v_cvt_pk_bf16_f32 v86, v93, s0
	v_mov_b32_dpp v88, v84 quad_perm:[2,3,0,1] row_mask:0xf bank_mask:0xf bound_ctrl:1
	v_mov_b32_dpp v89, v85 quad_perm:[2,3,0,1] row_mask:0xf bank_mask:0xf bound_ctrl:1
	v_add_f32_e32 v84, v84, v88
	v_add_f32_e32 v85, v85, v89
	v_fmac_f32_e32 v94, v88, v155
	ds_write_b16 v196, v86 offset:2448
	v_mov_b32_dpp v90, v84 row_half_mirror row_mask:0xf bank_mask:0xf bound_ctrl:1
	v_mov_b32_dpp v91, v85 row_half_mirror row_mask:0xf bank_mask:0xf bound_ctrl:1
	v_add_f32_e32 v84, v84, v90
	v_add_f32_e32 v85, v85, v91
	v_fmac_f32_e32 v94, v90, v180
	s_nop 0
	v_mov_b32_dpp v92, v84 row_ror:8 row_mask:0xf bank_mask:0xf bound_ctrl:1
	v_fmac_f32_e32 v94, v92, v181
	v_add_f32_e32 v80, v80, v94
	v_exp_f32_e32 v80, v80
	v_mov_b32_dpp v93, v85 row_ror:8 row_mask:0xf bank_mask:0xf bound_ctrl:1
	v_add_f32_e32 v84, v84, v92
	v_add_f32_e32 v85, v85, v93
	v_cvt_pk_bf16_f32 v80, v80, s0
	ds_write_b16 v196, v80 offset:2624
	v_fma_f32 v80, v87, v153, 0
	v_fmac_f32_e32 v80, v89, v155
	v_fmac_f32_e32 v80, v91, v180
	v_fmac_f32_e32 v80, v93, v181
	v_add_f32_e32 v80, v81, v80
	v_exp_f32_e32 v86, v80
	v_mul_f32_e32 v80, s24, v82
	v_mul_f32_e32 v81, s24, v83
	v_add_f32_e32 v84, v112, v84
	v_add_f32_e32 v85, v113, v85
	v_exp_f32_e64 v87, -|v80|
	v_exp_f32_e64 v88, -|v81|
	v_cvt_pk_bf16_f32 v89, v86, s0
	v_max_f32_e64 v80, -v80, 0
	v_add_f32_e32 v86, 1.0, v87
	v_add_f32_e32 v87, 1.0, v88
	v_log_f32_e32 v86, v86
	v_log_f32_e32 v87, v87
	v_max_f32_e64 v81, -v81, 0
	ds_write_b16 v196, v89 offset:2768
	v_add_f32_e32 v80, v80, v86
	v_add_f32_e32 v81, v81, v87
	s_nop 0
	v_fma_f32 v82, -v82, s24, -v80
	v_fma_f32 v83, -v83, s24, -v81
	v_sub_f32_e32 v80, v84, v80
	v_sub_f32_e32 v81, v85, v81
	s_nop 0
	v_mov_b32_dpp v86, v82 quad_perm:[1,0,3,2] row_mask:0xf bank_mask:0xf bound_ctrl:1
	v_mov_b32_dpp v87, v83 quad_perm:[1,0,3,2] row_mask:0xf bank_mask:0xf bound_ctrl:1
	v_add_f32_e32 v82, v82, v86
	v_add_f32_e32 v83, v83, v87
	v_fma_f32 v94, v86, v153, 0
	v_fma_f32 v86, v87, v153, 0
	v_mov_b32_dpp v88, v82 quad_perm:[2,3,0,1] row_mask:0xf bank_mask:0xf bound_ctrl:1
	v_mov_b32_dpp v89, v83 quad_perm:[2,3,0,1] row_mask:0xf bank_mask:0xf bound_ctrl:1
	v_add_f32_e32 v82, v82, v88
	v_add_f32_e32 v83, v83, v89
	v_fmac_f32_e32 v94, v88, v155
	v_fmac_f32_e32 v86, v89, v155
	v_mov_b32_dpp v90, v82 row_half_mirror row_mask:0xf bank_mask:0xf bound_ctrl:1
	v_mov_b32_dpp v91, v83 row_half_mirror row_mask:0xf bank_mask:0xf bound_ctrl:1
	v_add_f32_e32 v82, v82, v90
	v_add_f32_e32 v83, v83, v91
	v_fmac_f32_e32 v94, v90, v180
	v_fmac_f32_e32 v86, v91, v180
	v_mov_b32_dpp v92, v82 row_ror:8 row_mask:0xf bank_mask:0xf bound_ctrl:1
	v_mov_b32_dpp v93, v83 row_ror:8 row_mask:0xf bank_mask:0xf bound_ctrl:1
	v_fmac_f32_e32 v94, v92, v181
	v_fmac_f32_e32 v86, v93, v181
	v_add_f32_e32 v80, v80, v94
	v_add_f32_e32 v81, v81, v86
	v_exp_f32_e32 v80, v80
	v_exp_f32_e32 v81, v81
	v_add_f32_e32 v82, v82, v92
	v_add_f32_e32 v83, v83, v93
	v_cvt_pk_bf16_f32 v80, v80, s0
	v_add_f32_e32 v126, v84, v82
	v_add_f32_e32 v127, v85, v83
	v_cvt_pk_bf16_f32 v133, v81, s0
	ds_write_b16 v196, v80 offset:2592
	s_branch .LBB0_224

; #define MFMA(a, b, c) __builtin_amdgcn_mfma_f32_16x16x32_bf16((a), (b), (c), 0, 0, 0)
; __device__ void phase_attn(const Params& p, char* smem) {
;     ...
;         const int kbase = kt * 32;
;         const int knext = (kt > 0 ? kt - 1 : 0) * 32;
;         bf16x8 kfn[2][2], vf[4];
; #pragma unroll
;         for (int n = 0; n < 2; ++n)
; #pragma unroll
;           for (int ks = 0; ks < 2; ++ks)
;             kfn[n][ks] = *(const bf16x8*)(qk + (size_t)(b * S + knext + n * 16 + l15) * 1024 + 512 + h * 64 + ks * 32 + lq * 8);
; #pragma unroll
;         for (int nn = 0; nn < 4; ++nn)
;           vf[nn] = *(const bf16x8*)(vT + (size_t)(b * 512 + h * 64 + nn * 16 + l15) * S + kbase + lq * 8);
;         f32x4 s[2][2];
;         __builtin_amdgcn_s_setprio(1);
; #pragma unroll
;         for (int n = 0; n < 2; ++n) {
;           s[0][n] = f32x4{0.f, 0.f, 0.f, 0.f};
;           s[1][n] = f32x4{0.f, 0.f, 0.f, 0.f};
; #pragma unroll
;           for (int ks = 0; ks < 2; ++ks) {
;             s[0][n] = MFMA(qf[0][ks], kfc[n][ks], s[0][n]);
;             s[1][n] = MFMA(qf[1][ks], kfc[n][ks], s[1][n]);
;           }
;         }
;         __builtin_amdgcn_s_setprio(0);
;     ...
;         if (kbase + 31 >= q0) { ATT_TILE(true) } else { ATT_TILE(false) }
.LBB0_231:
	s_waitcnt vmcnt(3)
	v_mov_b64_e32 v[122:123], v[82:83]
	s_min_u32 s6, s72, 1
	s_waitcnt vmcnt(1)
	v_mov_b64_e32 v[126:127], v[90:91]
	v_mov_b64_e32 v[120:121], v[80:81]
	v_add_u32_e32 v80, s71, v201
	s_lshl_b32 s6, s6, 5
	v_mov_b64_e32 v[124:125], v[88:89]
	v_subrev_u32_e32 v88, s6, v80
	v_subrev_u32_e32 v80, 31, v88
	v_add_u32_e32 v88, -15, v88
	v_ashrrev_i32_e32 v81, 31, v80
	v_ashrrev_i32_e32 v89, 31, v88
	s_sub_i32 s36, s71, 31
	s_waitcnt vmcnt(0)
	v_mov_b64_e32 v[118:119], v[94:95]
	v_mov_b64_e32 v[114:115], v[86:87]
	v_lshlrev_b64 v[80:81], 11, v[80:81]
	v_lshlrev_b64 v[88:89], 11, v[88:89]
	v_lshl_add_u64 v[104:105], s[36:37], 1, v[134:135]
	v_mov_b64_e32 v[116:117], v[92:93]
	v_mov_b64_e32 v[112:113], v[84:85]
	v_lshl_add_u64 v[84:85], v[142:143], 0, v[80:81]
	v_lshl_add_u64 v[92:93], v[142:143], 0, v[88:89]
	v_lshl_add_u64 v[96:97], v[104:105], 0, v[156:157]
	v_lshl_add_u64 v[98:99], v[104:105], 0, v[158:159]
	v_lshl_add_u64 v[106:107], v[104:105], 0, v[160:161]
	v_lshl_add_u64 v[104:105], v[104:105], 0, v[162:163]
	global_load_dwordx4 v[80:83], v[84:85], off offset:1152
	s_nop 0
	global_load_dwordx4 v[84:87], v[84:85], off offset:1216
	s_nop 0
	global_load_dwordx4 v[88:91], v[92:93], off offset:1152
	s_nop 0
	global_load_dwordx4 v[92:95], v[92:93], off offset:1216
	s_nop 0
	global_load_dwordx4 v[100:103], v[96:97], off
	s_nop 0
	global_load_dwordx4 v[96:99], v[98:99], off
	s_nop 0
	global_load_dwordx4 v[108:111], v[106:107], off
	s_nop 0
	global_load_dwordx4 v[104:107], v[104:105], off
	s_setprio 1
	v_mfma_f32_16x16x32_bf16 v[174:177], v[64:67], v[120:123], 0
	v_mfma_f32_16x16x32_bf16 v[202:205], v[72:75], v[120:123], 0
	v_mfma_f32_16x16x32_bf16 v[120:123], v[68:71], v[112:115], v[174:177]
	v_mfma_f32_16x16x32_bf16 v[112:115], v[76:79], v[112:115], v[202:205]
	v_mfma_f32_16x16x32_bf16 v[174:177], v[64:67], v[124:127], 0
	v_mfma_f32_16x16x32_bf16 v[202:205], v[72:75], v[124:127], 0
	v_mfma_f32_16x16x32_bf16 v[124:127], v[68:71], v[116:119], v[174:177]
	v_mfma_f32_16x16x32_bf16 v[116:119], v[76:79], v[116:119], v[202:205]
	s_setprio 0
	s_cmp_lt_u32 s71, s70
	s_mov_b64 s[6:7], -1
	s_cbranch_scc1 .LBB0_233
	s_nop 2
	v_mul_f32_e32 v170, 0x3e38aa3b, v124
	v_exp_f32_e64 v171, -|v170|
	v_add_u32_e32 v174, s71, v151
	v_mul_f32_e32 v175, 0x3e38aa3b, v125
	v_subrev_u32_e32 v133, 31, v174
	v_add_f32_e32 v171, 1.0, v171
	v_log_f32_e32 v171, v171
	v_add_u32_e32 v206, -15, v174
	v_exp_f32_e64 v174, -|v175|
	v_max_f32_e64 v170, -v170, 0
	v_add_f32_e32 v170, v170, v171
	v_fma_f32 v176, v124, s41, -v170
	v_sub_f32_e32 v203, v172, v170
	v_add_f32_e32 v170, 1.0, v174
	v_log_f32_e32 v170, v170
	v_mul_f32_e32 v174, 0x3e38aa3b, v120
	v_max_f32_e64 v171, -v175, 0
	v_exp_f32_e64 v175, -|v174|
	v_add_f32_e32 v170, v171, v170
	v_fma_f32 v171, v125, s41, -v170
	v_sub_f32_e32 v204, v173, v170
	v_add_f32_e32 v170, 1.0, v175
	v_mul_f32_e32 v175, 0x3e38aa3b, v121
	v_log_f32_e32 v170, v170
	v_exp_f32_e64 v177, -|v175|
	v_max_f32_e64 v174, -v174, 0
	v_cmp_lt_u32_e32 vcc, v148, v206
	v_add_f32_e32 v205, v174, v170
	v_add_f32_e32 v170, 1.0, v177
	v_cmp_lt_u32_e64 s[6:7], v206, v148
	v_log_f32_e32 v210, v170
	v_cndmask_b32_e64 v171, v171, 0, vcc
	v_cndmask_b32_e64 v170, 0, v176, s[6:7]
	v_max_f32_e64 v209, -v175, 0
	v_mov_b32_dpp v175, v171 quad_perm:[1,0,3,2] row_mask:0xf bank_mask:0xf bound_ctrl:1
	v_mov_b32_dpp v174, v170 quad_perm:[1,0,3,2] row_mask:0xf bank_mask:0xf bound_ctrl:1
	v_add_f32_e32 v170, v170, v174
	v_add_f32_e32 v171, v171, v175
	v_fma_f32 v211, v174, v153, 0
	v_fma_f32 v175, v175, v153, 0
	v_mov_b32_dpp v176, v170 quad_perm:[2,3,0,1] row_mask:0xf bank_mask:0xf bound_ctrl:1
	v_mov_b32_dpp v177, v171 quad_perm:[2,3,0,1] row_mask:0xf bank_mask:0xf bound_ctrl:1
	v_add_f32_e32 v170, v170, v176
	v_add_f32_e32 v171, v171, v177
	v_fmac_f32_e32 v211, v176, v155
	v_fmac_f32_e32 v175, v177, v155
	v_mov_b32_dpp v178, v170 row_half_mirror row_mask:0xf bank_mask:0xf bound_ctrl:1
	v_mov_b32_dpp v179, v171 row_half_mirror row_mask:0xf bank_mask:0xf bound_ctrl:1
	v_add_f32_e32 v170, v170, v178
	v_add_f32_e32 v171, v171, v179
	v_fmac_f32_e32 v211, v178, v180
	v_fmac_f32_e32 v175, v179, v180
	v_mov_b32_dpp v202, v170 row_ror:8 row_mask:0xf bank_mask:0xf bound_ctrl:1
	v_fmac_f32_e32 v211, v202, v181
	v_add_f32_e32 v174, v203, v211
	v_mov_b32_dpp v203, v171 row_ror:8 row_mask:0xf bank_mask:0xf bound_ctrl:1
	v_exp_f32_e32 v174, v174
	v_fmac_f32_e32 v175, v203, v181
	v_add_f32_e32 v175, v204, v175
	v_exp_f32_e32 v175, v175
	v_cvt_pk_bf16_f32 v174, v174, s0
	v_cndmask_b32_e64 v174, 0, v174, s[6:7]
	v_add_f32_e32 v209, v209, v210
	ds_write_b16 v196, v174 offset:32
	v_cvt_pk_bf16_f32 v174, v175, s0
	v_fma_f32 v208, v120, s41, -v205
	v_fma_f32 v176, v121, s41, -v209
	v_cndmask_b32_e64 v210, v174, 0, vcc
	v_cmp_lt_u32_e64 s[6:7], v148, v133
	v_cmp_lt_u32_e32 vcc, v133, v148
	v_add_f32_e32 v170, v170, v202
	v_add_f32_e32 v171, v171, v203
	v_cndmask_b32_e64 v175, v176, 0, s[6:7]
	v_cndmask_b32_e32 v174, 0, v208, vcc
	v_add_f32_e32 v170, v172, v170
	v_add_f32_e32 v171, v173, v171
	v_mov_b32_dpp v177, v175 quad_perm:[1,0,3,2] row_mask:0xf bank_mask:0xf bound_ctrl:1
	v_mov_b32_dpp v176, v174 quad_perm:[1,0,3,2] row_mask:0xf bank_mask:0xf bound_ctrl:1
	v_add_f32_e32 v174, v174, v176
	v_add_f32_e32 v175, v175, v177
	v_fma_f32 v208, v176, v153, 0
	v_sub_f32_e32 v176, v170, v205
	v_mov_b32_dpp v178, v174 quad_perm:[2,3,0,1] row_mask:0xf bank_mask:0xf bound_ctrl:1
	v_mov_b32_dpp v179, v175 quad_perm:[2,3,0,1] row_mask:0xf bank_mask:0xf bound_ctrl:1
	v_add_f32_e32 v174, v174, v178
	v_add_f32_e32 v175, v175, v179
	v_fmac_f32_e32 v208, v178, v155
	v_cmp_lt_u32_e64 s[8:9], v206, v129
; __device__ void phase_attn(const Params& p, char* smem) {
;     ...
;         if (kbase + 31 >= q0) { ATT_TILE(true) } else { ATT_TILE(false) }
	v_mov_b32_dpp v202, v174 row_half_mirror row_mask:0xf bank_mask:0xf bound_ctrl:1
	v_mov_b32_dpp v203, v175 row_half_mirror row_mask:0xf bank_mask:0xf bound_ctrl:1
	v_add_f32_e32 v174, v174, v202
	v_add_f32_e32 v175, v175, v203
	v_fmac_f32_e32 v208, v202, v180
	v_cmp_lt_u32_e64 s[10:11], v206, v150
	v_mov_b32_dpp v204, v174 row_ror:8 row_mask:0xf bank_mask:0xf bound_ctrl:1
	v_fmac_f32_e32 v208, v204, v181
	v_add_f32_e32 v176, v176, v208
	v_exp_f32_e32 v176, v176
	v_mov_b32_dpp v205, v175 row_ror:8 row_mask:0xf bank_mask:0xf bound_ctrl:1
	v_add_f32_e32 v174, v174, v204
	v_add_f32_e32 v175, v175, v205
	ds_write_b16 v196, v210 offset:176
	v_cvt_pk_bf16_f32 v176, v176, s0
	v_cndmask_b32_e32 v176, 0, v176, vcc
	ds_write_b16 v196, v176
	v_fma_f32 v176, v177, v153, 0
	v_fmac_f32_e32 v176, v179, v155
	v_fmac_f32_e32 v176, v203, v180
	v_fmac_f32_e32 v176, v205, v181
	v_sub_f32_e32 v177, v171, v209
	v_add_f32_e32 v178, v177, v176
	v_mul_f32_e32 v176, s24, v126
	v_mul_f32_e32 v177, s24, v127
	v_add_f32_e32 v170, v170, v174
	v_add_f32_e32 v171, v171, v175
	v_exp_f32_e64 v179, -|v176|
	v_exp_f32_e64 v202, -|v177|
	v_exp_f32_e32 v178, v178
	v_max_f32_e64 v176, -v176, 0
	v_add_f32_e32 v174, 1.0, v179
	v_add_f32_e32 v175, 1.0, v202
	v_log_f32_e32 v174, v174
	v_log_f32_e32 v175, v175
	v_max_f32_e64 v177, -v177, 0
	v_cvt_pk_bf16_f32 v209, v178, s0
	v_add_f32_e32 v174, v176, v174
	v_add_f32_e32 v175, v177, v175
	s_nop 0
	v_fma_f32 v176, -v126, s24, -v174
	v_fma_f32 v177, -v127, s24, -v175
	v_sub_f32_e32 v174, v168, v174
	v_sub_f32_e32 v175, v169, v175
	v_cndmask_b32_e64 v177, 0, v177, s[8:9]
	v_cndmask_b32_e64 v176, 0, v176, s[10:11]
	s_nop 0
	v_mov_b32_dpp v179, v177 quad_perm:[1,0,3,2] row_mask:0xf bank_mask:0xf bound_ctrl:1
	v_mov_b32_dpp v178, v176 quad_perm:[1,0,3,2] row_mask:0xf bank_mask:0xf bound_ctrl:1
	v_add_f32_e32 v176, v176, v178
	v_add_f32_e32 v177, v177, v179
	v_fma_f32 v210, v178, v153, 0
	v_cndmask_b32_e64 v178, v209, 0, s[6:7]
	v_mov_b32_dpp v202, v176 quad_perm:[2,3,0,1] row_mask:0xf bank_mask:0xf bound_ctrl:1
	v_mov_b32_dpp v203, v177 quad_perm:[2,3,0,1] row_mask:0xf bank_mask:0xf bound_ctrl:1
	v_add_f32_e32 v176, v176, v202
	v_add_f32_e32 v177, v177, v203
	v_fmac_f32_e32 v210, v202, v155
	ds_write_b16 v196, v178 offset:144
	v_mov_b32_dpp v204, v176 row_half_mirror row_mask:0xf bank_mask:0xf bound_ctrl:1
	v_mov_b32_dpp v205, v177 row_half_mirror row_mask:0xf bank_mask:0xf bound_ctrl:1
	v_add_f32_e32 v176, v176, v204
	v_add_f32_e32 v177, v177, v205
	v_fmac_f32_e32 v210, v204, v180
	v_cmp_lt_u32_e64 s[6:7], v133, v129
	v_mov_b32_dpp v208, v176 row_ror:8 row_mask:0xf bank_mask:0xf bound_ctrl:1
	v_fmac_f32_e32 v210, v208, v181
	v_add_f32_e32 v174, v174, v210
	v_exp_f32_e32 v174, v174
	v_mov_b32_dpp v209, v177 row_ror:8 row_mask:0xf bank_mask:0xf bound_ctrl:1
	v_add_f32_e32 v176, v176, v208
	v_add_f32_e32 v177, v177, v209
	v_cvt_pk_bf16_f32 v174, v174, s0
	v_cndmask_b32_e64 v174, 0, v174, s[10:11]
	ds_write_b16 v196, v174 offset:320
	v_fma_f32 v174, v179, v153, 0
	v_fmac_f32_e32 v174, v203, v155
	v_fmac_f32_e32 v174, v205, v180
	v_fmac_f32_e32 v174, v209, v181
	v_add_f32_e32 v174, v175, v174
	v_exp_f32_e32 v178, v174
	v_mul_f32_e32 v174, s24, v122
	v_mul_f32_e32 v175, s24, v123
	v_add_f32_e32 v176, v168, v176
	v_add_f32_e32 v177, v169, v177
	v_exp_f32_e64 v179, -|v174|
	v_exp_f32_e64 v202, -|v175|
	v_cvt_pk_bf16_f32 v203, v178, s0
	v_max_f32_e64 v174, -v174, 0
	v_add_f32_e32 v178, 1.0, v179
	v_add_f32_e32 v179, 1.0, v202
	v_log_f32_e32 v178, v178
	v_log_f32_e32 v179, v179
	v_max_f32_e64 v175, -v175, 0
	v_cndmask_b32_e64 v211, 0, v203, s[8:9]
	v_cmp_lt_u32_e64 s[8:9], v133, v150
	v_add_f32_e32 v174, v174, v178
	v_add_f32_e32 v175, v175, v179
	ds_write_b16 v196, v211 offset:464
	v_fma_f32 v178, -v122, s24, -v174
	v_fma_f32 v179, -v123, s24, -v175
	v_sub_f32_e32 v174, v176, v174
	v_sub_f32_e32 v175, v177, v175
	v_cndmask_b32_e64 v179, 0, v179, s[6:7]
	v_cndmask_b32_e64 v178, 0, v178, s[8:9]
	s_nop 0
	v_mov_b32_dpp v203, v179 quad_perm:[1,0,3,2] row_mask:0xf bank_mask:0xf bound_ctrl:1
	v_mov_b32_dpp v202, v178 quad_perm:[1,0,3,2] row_mask:0xf bank_mask:0xf bound_ctrl:1
	v_add_f32_e32 v178, v178, v202
	v_add_f32_e32 v179, v179, v203
	v_fma_f32 v212, v202, v153, 0
	s_nop 0
	v_mov_b32_dpp v204, v178 quad_perm:[2,3,0,1] row_mask:0xf bank_mask:0xf bound_ctrl:1
	v_mov_b32_dpp v205, v179 quad_perm:[2,3,0,1] row_mask:0xf bank_mask:0xf bound_ctrl:1
	v_add_f32_e32 v178, v178, v204
	v_add_f32_e32 v179, v179, v205
	v_fmac_f32_e32 v212, v204, v155
	s_nop 0
	v_mov_b32_dpp v208, v178 row_half_mirror row_mask:0xf bank_mask:0xf bound_ctrl:1
	v_mov_b32_dpp v209, v179 row_half_mirror row_mask:0xf bank_mask:0xf bound_ctrl:1
	v_add_f32_e32 v178, v178, v208
	v_add_f32_e32 v179, v179, v209
	v_fmac_f32_e32 v212, v208, v180
	s_nop 0
	v_mov_b32_dpp v210, v178 row_ror:8 row_mask:0xf bank_mask:0xf bound_ctrl:1
	v_fmac_f32_e32 v212, v210, v181
	v_add_f32_e32 v174, v174, v212
	v_exp_f32_e32 v174, v174
	v_mov_b32_dpp v211, v179 row_ror:8 row_mask:0xf bank_mask:0xf bound_ctrl:1
	v_add_f32_e32 v178, v178, v210
	v_add_f32_e32 v179, v179, v211
	v_cvt_pk_bf16_f32 v174, v174, s0
	v_cndmask_b32_e64 v174, 0, v174, s[8:9]
	ds_write_b16 v196, v174 offset:288
	v_fma_f32 v174, v203, v153, 0
	v_mul_f32_e32 v202, s24, v116
	v_mul_f32_e32 v203, s24, v117
	v_fmac_f32_e32 v174, v205, v155
	v_exp_f32_e64 v204, -|v202|
	v_exp_f32_e64 v208, -|v203|
	v_fmac_f32_e32 v174, v209, v180
	v_fmac_f32_e32 v174, v211, v181
	v_add_f32_e32 v174, v175, v174
	v_exp_f32_e32 v205, v174
	v_add_f32_e32 v174, v176, v178
	v_add_f32_e32 v175, v177, v179
	v_add_f32_e32 v176, 1.0, v204
	v_add_f32_e32 v177, 1.0, v208
; __device__ void phase_attn(const Params& p, char* smem) {
;     ...
;         if (kbase + 31 >= q0) { ATT_TILE(true) } else { ATT_TILE(false) }
	v_log_f32_e32 v176, v176
	v_log_f32_e32 v177, v177
	v_max_f32_e64 v178, -v202, 0
	v_max_f32_e64 v179, -v203, 0
	v_cmp_lt_u32_e64 s[8:9], v206, v131
	v_add_f32_e32 v176, v178, v176
	v_add_f32_e32 v177, v179, v177
	v_cvt_pk_bf16_f32 v210, v205, s0
	v_sub_f32_e32 v178, v166, v176
	v_sub_f32_e32 v179, v167, v177
	v_fma_f32 v176, -v116, s24, -v176
	v_fma_f32 v177, -v117, s24, -v177
	s_nop 0
	v_cndmask_b32_e64 v177, 0, v177, s[8:9]
	v_cndmask_b32_e32 v176, 0, v176, vcc
	s_nop 0
	v_mov_b32_dpp v203, v177 quad_perm:[1,0,3,2] row_mask:0xf bank_mask:0xf bound_ctrl:1
	v_mov_b32_dpp v202, v176 quad_perm:[1,0,3,2] row_mask:0xf bank_mask:0xf bound_ctrl:1
	v_add_f32_e32 v176, v176, v202
	v_add_f32_e32 v177, v177, v203
	v_fma_f32 v212, v203, v153, 0
	v_cndmask_b32_e64 v203, 0, v210, s[6:7]
	v_mov_b32_dpp v205, v177 quad_perm:[2,3,0,1] row_mask:0xf bank_mask:0xf bound_ctrl:1
	v_mov_b32_dpp v204, v176 quad_perm:[2,3,0,1] row_mask:0xf bank_mask:0xf bound_ctrl:1
	v_add_f32_e32 v176, v176, v204
	v_add_f32_e32 v177, v177, v205
	v_fmac_f32_e32 v212, v205, v155
	ds_write_b16 v196, v203 offset:432
	v_mov_b32_dpp v209, v177 row_half_mirror row_mask:0xf bank_mask:0xf bound_ctrl:1
	v_mov_b32_dpp v208, v176 row_half_mirror row_mask:0xf bank_mask:0xf bound_ctrl:1
	v_add_f32_e32 v176, v176, v208
	v_add_f32_e32 v177, v177, v209
	v_fmac_f32_e32 v212, v209, v180
	v_cmp_lt_u32_e64 s[6:7], v133, v152
	v_mov_b32_dpp v211, v177 row_ror:8 row_mask:0xf bank_mask:0xf bound_ctrl:1
	v_fmac_f32_e32 v212, v211, v181
	v_add_f32_e32 v179, v179, v212
	v_exp_f32_e32 v179, v179
	v_mov_b32_dpp v210, v176 row_ror:8 row_mask:0xf bank_mask:0xf bound_ctrl:1
	v_add_f32_e32 v176, v176, v210
	v_add_f32_e32 v177, v177, v211
	v_cvt_pk_bf16_f32 v179, v179, s0
	v_cndmask_b32_e64 v179, 0, v179, s[8:9]
	ds_write_b16 v196, v179 offset:2480
	v_fma_f32 v179, v202, v153, 0
	v_fmac_f32_e32 v179, v204, v155
	v_fmac_f32_e32 v179, v208, v180
	v_fmac_f32_e32 v179, v210, v181
	v_add_f32_e32 v178, v178, v179
	v_exp_f32_e32 v202, v178
	v_mul_f32_e32 v178, s24, v112
	v_mul_f32_e32 v179, s24, v113
	v_add_f32_e32 v176, v166, v176
	v_add_f32_e32 v177, v167, v177
	v_exp_f32_e64 v203, -|v178|
	v_exp_f32_e64 v204, -|v179|
	v_cvt_pk_bf16_f32 v205, v202, s0
	v_max_f32_e64 v178, -v178, 0
	v_add_f32_e32 v202, 1.0, v203
	v_add_f32_e32 v203, 1.0, v204
	v_log_f32_e32 v202, v202
	v_log_f32_e32 v203, v203
	v_max_f32_e64 v179, -v179, 0
	v_cndmask_b32_e32 v213, 0, v205, vcc
	v_cmp_lt_u32_e32 vcc, v133, v131
	v_add_f32_e32 v178, v178, v202
	v_add_f32_e32 v179, v179, v203
	ds_write_b16 v196, v213 offset:2336
	v_fma_f32 v202, -v112, s24, -v178
	v_fma_f32 v203, -v113, s24, -v179
	v_sub_f32_e32 v178, v176, v178
	v_sub_f32_e32 v179, v177, v179
	v_cndmask_b32_e32 v203, 0, v203, vcc
	v_cndmask_b32_e64 v202, 0, v202, s[6:7]
	v_cmp_lt_u32_e64 s[8:9], v206, v154
	v_mov_b32_dpp v205, v203 quad_perm:[1,0,3,2] row_mask:0xf bank_mask:0xf bound_ctrl:1
	v_mov_b32_dpp v204, v202 quad_perm:[1,0,3,2] row_mask:0xf bank_mask:0xf bound_ctrl:1
	v_add_f32_e32 v202, v202, v204
	v_add_f32_e32 v203, v203, v205
	v_fma_f32 v214, v204, v153, 0
	s_nop 0
	v_mov_b32_dpp v208, v202 quad_perm:[2,3,0,1] row_mask:0xf bank_mask:0xf bound_ctrl:1
	v_mov_b32_dpp v209, v203 quad_perm:[2,3,0,1] row_mask:0xf bank_mask:0xf bound_ctrl:1
	v_add_f32_e32 v202, v202, v208
	v_add_f32_e32 v203, v203, v209
	v_fmac_f32_e32 v214, v208, v155
	s_nop 0
	v_mov_b32_dpp v210, v202 row_half_mirror row_mask:0xf bank_mask:0xf bound_ctrl:1
	v_mov_b32_dpp v211, v203 row_half_mirror row_mask:0xf bank_mask:0xf bound_ctrl:1
	v_add_f32_e32 v202, v202, v210
	v_add_f32_e32 v203, v203, v211
	v_fmac_f32_e32 v214, v210, v180
	s_nop 0
	v_mov_b32_dpp v212, v202 row_ror:8 row_mask:0xf bank_mask:0xf bound_ctrl:1
	v_fmac_f32_e32 v214, v212, v181
	v_add_f32_e32 v178, v178, v214
	v_exp_f32_e32 v178, v178
	v_mov_b32_dpp v213, v203 row_ror:8 row_mask:0xf bank_mask:0xf bound_ctrl:1
	v_add_f32_e32 v202, v202, v212
	v_add_f32_e32 v203, v203, v213
	v_cvt_pk_bf16_f32 v178, v178, s0
	v_cndmask_b32_e64 v178, 0, v178, s[6:7]
	ds_write_b16 v196, v178 offset:2304
	v_fma_f32 v178, v205, v153, 0
	v_fmac_f32_e32 v178, v209, v155
	v_fmac_f32_e32 v178, v211, v180
	v_fmac_f32_e32 v178, v213, v181
	v_add_f32_e32 v204, v179, v178
	v_mul_f32_e32 v178, s24, v118
	v_mul_f32_e32 v179, s24, v119
	v_add_f32_e32 v176, v176, v202
	v_add_f32_e32 v177, v177, v203
	v_exp_f32_e64 v205, -|v178|
	v_exp_f32_e64 v208, -|v179|
	v_exp_f32_e32 v204, v204
	v_max_f32_e64 v178, -v178, 0
	v_add_f32_e32 v202, 1.0, v205
	v_add_f32_e32 v203, 1.0, v208
	v_log_f32_e32 v202, v202
	v_log_f32_e32 v203, v203
	v_max_f32_e64 v179, -v179, 0
	v_cmp_lt_u32_e64 s[6:7], v206, v149
	v_cvt_pk_bf16_f32 v213, v204, s0
	v_add_f32_e32 v178, v178, v202
	v_add_f32_e32 v179, v179, v203
	s_nop 0
	v_fma_f32 v202, -v118, s24, -v178
	v_fma_f32 v203, -v119, s24, -v179
	v_sub_f32_e32 v178, v164, v178
	v_sub_f32_e32 v179, v165, v179
	v_cndmask_b32_e64 v203, 0, v203, s[6:7]
	v_cndmask_b32_e64 v202, 0, v202, s[8:9]
	s_nop 0
	v_mov_b32_dpp v205, v203 quad_perm:[1,0,3,2] row_mask:0xf bank_mask:0xf bound_ctrl:1
	v_mov_b32_dpp v204, v202 quad_perm:[1,0,3,2] row_mask:0xf bank_mask:0xf bound_ctrl:1
	v_add_f32_e32 v202, v202, v204
	v_add_f32_e32 v203, v203, v205
	v_fma_f32 v206, v204, v153, 0
	v_cndmask_b32_e32 v204, 0, v213, vcc
	v_mov_b32_dpp v208, v202 quad_perm:[2,3,0,1] row_mask:0xf bank_mask:0xf bound_ctrl:1
	v_mov_b32_dpp v209, v203 quad_perm:[2,3,0,1] row_mask:0xf bank_mask:0xf bound_ctrl:1
	v_add_f32_e32 v202, v202, v208
	v_add_f32_e32 v203, v203, v209
	v_fmac_f32_e32 v206, v208, v155
	ds_write_b16 v196, v204 offset:2448
	v_mov_b32_dpp v210, v202 row_half_mirror row_mask:0xf bank_mask:0xf bound_ctrl:1
; __device__ void phase_attn(const Params& p, char* smem) {
;     ...
;         if (kbase + 31 >= q0) { ATT_TILE(true) } else { ATT_TILE(false) }
	v_mov_b32_dpp v211, v203 row_half_mirror row_mask:0xf bank_mask:0xf bound_ctrl:1
	v_add_f32_e32 v202, v202, v210
	v_add_f32_e32 v203, v203, v211
	v_fmac_f32_e32 v206, v210, v180
	v_cmp_lt_u32_e32 vcc, v133, v149
	v_mov_b32_dpp v212, v202 row_ror:8 row_mask:0xf bank_mask:0xf bound_ctrl:1
	v_fmac_f32_e32 v206, v212, v181
	v_add_f32_e32 v178, v178, v206
	v_exp_f32_e32 v178, v178
	v_mov_b32_dpp v213, v203 row_ror:8 row_mask:0xf bank_mask:0xf bound_ctrl:1
	v_add_f32_e32 v202, v202, v212
	v_add_f32_e32 v203, v203, v213
	v_cvt_pk_bf16_f32 v178, v178, s0
	v_cndmask_b32_e64 v178, 0, v178, s[8:9]
	ds_write_b16 v196, v178 offset:2624
	v_fma_f32 v178, v205, v153, 0
	v_fmac_f32_e32 v178, v209, v155
	v_fmac_f32_e32 v178, v211, v180
	v_fmac_f32_e32 v178, v213, v181
	v_add_f32_e32 v178, v179, v178
	v_exp_f32_e32 v204, v178
	v_mul_f32_e32 v178, s24, v114
	v_mul_f32_e32 v179, s24, v115
	v_add_f32_e32 v202, v164, v202
	v_add_f32_e32 v203, v165, v203
	v_exp_f32_e64 v205, -|v178|
	v_exp_f32_e64 v206, -|v179|
	v_cvt_pk_bf16_f32 v208, v204, s0
	v_max_f32_e64 v178, -v178, 0
	v_add_f32_e32 v204, 1.0, v205
	v_add_f32_e32 v205, 1.0, v206
	v_log_f32_e32 v204, v204
	v_log_f32_e32 v205, v205
	v_max_f32_e64 v179, -v179, 0
	v_cndmask_b32_e64 v206, 0, v208, s[6:7]
	v_cmp_lt_u32_e64 s[6:7], v133, v154
	v_add_f32_e32 v178, v178, v204
	v_add_f32_e32 v179, v179, v205
	ds_write_b16 v196, v206 offset:2768
	v_fma_f32 v204, -v114, s24, -v178
	v_fma_f32 v205, -v115, s24, -v179
	v_sub_f32_e32 v178, v202, v178
	v_sub_f32_e32 v179, v203, v179
	v_cndmask_b32_e32 v205, 0, v205, vcc
	v_cndmask_b32_e64 v204, 0, v204, s[6:7]
	s_nop 0
	v_mov_b32_dpp v209, v205 quad_perm:[1,0,3,2] row_mask:0xf bank_mask:0xf bound_ctrl:1
	v_mov_b32_dpp v208, v204 quad_perm:[1,0,3,2] row_mask:0xf bank_mask:0xf bound_ctrl:1
	v_add_f32_e32 v204, v204, v208
	v_add_f32_e32 v205, v205, v209
	v_fma_f32 v133, v208, v153, 0
	s_nop 0
	v_mov_b32_dpp v210, v204 quad_perm:[2,3,0,1] row_mask:0xf bank_mask:0xf bound_ctrl:1
	v_mov_b32_dpp v211, v205 quad_perm:[2,3,0,1] row_mask:0xf bank_mask:0xf bound_ctrl:1
	v_add_f32_e32 v204, v204, v210
	v_add_f32_e32 v205, v205, v211
	v_fmac_f32_e32 v133, v210, v155
	s_nop 0
	v_mov_b32_dpp v212, v204 row_half_mirror row_mask:0xf bank_mask:0xf bound_ctrl:1
	v_mov_b32_dpp v213, v205 row_half_mirror row_mask:0xf bank_mask:0xf bound_ctrl:1
	v_add_f32_e32 v204, v204, v212
	v_add_f32_e32 v205, v205, v213
	v_fmac_f32_e32 v133, v212, v180
	s_nop 0
	v_mov_b32_dpp v214, v204 row_ror:8 row_mask:0xf bank_mask:0xf bound_ctrl:1
	v_fmac_f32_e32 v133, v214, v181
	v_add_f32_e32 v133, v178, v133
	v_fma_f32 v178, v209, v153, 0
	v_fmac_f32_e32 v178, v211, v155
	v_mov_b32_dpp v215, v205 row_ror:8 row_mask:0xf bank_mask:0xf bound_ctrl:1
	v_fmac_f32_e32 v178, v213, v180
	v_exp_f32_e32 v133, v133
	v_fmac_f32_e32 v178, v215, v181
	v_add_f32_e32 v178, v179, v178
	v_exp_f32_e32 v206, v178
	v_cvt_pk_bf16_f32 v133, v133, s0
	v_cndmask_b32_e64 v133, 0, v133, s[6:7]
	v_add_f32_e32 v204, v204, v214
	v_add_f32_e32 v205, v205, v215
	ds_write_b16 v196, v133 offset:2592
	v_cvt_pk_bf16_f32 v133, v206, s0
	v_add_f32_e32 v178, v202, v204
	v_add_f32_e32 v179, v203, v205
	v_cndmask_b32_e32 v133, 0, v133, vcc
	s_mov_b64 s[6:7], 0
.LBB0_233:
	s_andn2_b64 vcc, exec, s[6:7]
	s_cbranch_vccnz .LBB0_230
	s_nop 0
	v_mul_f32_e32 v170, s24, v124
	v_mul_f32_e32 v171, s24, v125
	s_nop 0
	v_exp_f32_e64 v133, -|v170|
	v_exp_f32_e64 v174, -|v171|
	v_max_f32_e64 v170, -v170, 0
	v_max_f32_e64 v171, -v171, 0
	v_add_f32_e32 v133, 1.0, v133
	v_add_f32_e32 v175, 1.0, v174
	v_log_f32_e32 v174, v133
	v_log_f32_e32 v175, v175
	s_nop 0
	v_add_f32_e32 v170, v170, v174
	v_add_f32_e32 v171, v171, v175
	s_nop 0
	v_fma_f32 v124, -v124, s24, -v170
	v_fma_f32 v125, -v125, s24, -v171
	v_sub_f32_e32 v170, v172, v170
	v_sub_f32_e32 v171, v173, v171
	s_nop 0
	v_mov_b32_dpp v174, v124 quad_perm:[1,0,3,2] row_mask:0xf bank_mask:0xf bound_ctrl:1
	v_mov_b32_dpp v175, v125 quad_perm:[1,0,3,2] row_mask:0xf bank_mask:0xf bound_ctrl:1
	v_add_f32_e32 v124, v124, v174
	v_add_f32_e32 v125, v125, v175
	v_fma_f32 v133, v174, v153, 0
	s_nop 0
	v_mov_b32_dpp v176, v124 quad_perm:[2,3,0,1] row_mask:0xf bank_mask:0xf bound_ctrl:1
	v_mov_b32_dpp v177, v125 quad_perm:[2,3,0,1] row_mask:0xf bank_mask:0xf bound_ctrl:1
	v_add_f32_e32 v124, v124, v176
	v_add_f32_e32 v125, v125, v177
	v_fmac_f32_e32 v133, v176, v155
	s_nop 0
	v_mov_b32_dpp v178, v124 row_half_mirror row_mask:0xf bank_mask:0xf bound_ctrl:1
	v_mov_b32_dpp v179, v125 row_half_mirror row_mask:0xf bank_mask:0xf bound_ctrl:1
	v_add_f32_e32 v124, v124, v178
	v_add_f32_e32 v125, v125, v179
	v_fmac_f32_e32 v133, v178, v180
	s_nop 0
	v_mov_b32_dpp v202, v124 row_ror:8 row_mask:0xf bank_mask:0xf bound_ctrl:1
	v_fmac_f32_e32 v133, v202, v181
	v_add_f32_e32 v133, v170, v133
	v_exp_f32_e32 v133, v133
	v_mov_b32_dpp v203, v125 row_ror:8 row_mask:0xf bank_mask:0xf bound_ctrl:1
	v_add_f32_e32 v124, v124, v202
	v_add_f32_e32 v125, v125, v203
	v_cvt_pk_bf16_f32 v133, v133, s0
	ds_write_b16 v196, v133 offset:32
	v_fma_f32 v133, v175, v153, 0
	v_fmac_f32_e32 v133, v177, v155
	v_fmac_f32_e32 v133, v179, v180
	v_fmac_f32_e32 v133, v203, v181
	v_add_f32_e32 v133, v171, v133
	v_mul_f32_e32 v170, s24, v120
	v_mul_f32_e32 v171, s24, v121
	v_add_f32_e32 v124, v172, v124
	v_add_f32_e32 v125, v173, v125
	v_exp_f32_e64 v174, -|v170|
	v_exp_f32_e64 v175, -|v171|
	v_max_f32_e64 v170, -v170, 0
	v_max_f32_e64 v171, -v171, 0
	v_add_f32_e32 v172, 1.0, v174
	v_add_f32_e32 v173, 1.0, v175
	v_log_f32_e32 v172, v172
	v_log_f32_e32 v173, v173
	v_exp_f32_e32 v133, v133
	v_add_f32_e32 v170, v170, v172
	v_add_f32_e32 v171, v171, v173
	s_nop 0
; __device__ void phase_attn(const Params& p, char* smem) {
;     ...
;         if (kbase + 31 >= q0) { ATT_TILE(true) } else { ATT_TILE(false) }
	v_fma_f32 v120, -v120, s24, -v170
	v_fma_f32 v121, -v121, s24, -v171
	v_sub_f32_e32 v170, v124, v170
	v_sub_f32_e32 v171, v125, v171
	v_cvt_pk_bf16_f32 v133, v133, s0
	v_mov_b32_dpp v172, v120 quad_perm:[1,0,3,2] row_mask:0xf bank_mask:0xf bound_ctrl:1
	v_mov_b32_dpp v173, v121 quad_perm:[1,0,3,2] row_mask:0xf bank_mask:0xf bound_ctrl:1
	v_add_f32_e32 v120, v120, v172
	v_add_f32_e32 v121, v121, v173
	v_fma_f32 v179, v172, v153, 0
	ds_write_b16 v196, v133 offset:176
	v_mov_b32_dpp v174, v120 quad_perm:[2,3,0,1] row_mask:0xf bank_mask:0xf bound_ctrl:1
	v_mov_b32_dpp v175, v121 quad_perm:[2,3,0,1] row_mask:0xf bank_mask:0xf bound_ctrl:1
	v_add_f32_e32 v120, v120, v174
	v_add_f32_e32 v121, v121, v175
	v_fmac_f32_e32 v179, v174, v155
	s_nop 0
	v_mov_b32_dpp v176, v120 row_half_mirror row_mask:0xf bank_mask:0xf bound_ctrl:1
	v_mov_b32_dpp v177, v121 row_half_mirror row_mask:0xf bank_mask:0xf bound_ctrl:1
	v_add_f32_e32 v120, v120, v176
	v_add_f32_e32 v121, v121, v177
	v_fmac_f32_e32 v179, v176, v180
	s_nop 0
	v_mov_b32_dpp v178, v120 row_ror:8 row_mask:0xf bank_mask:0xf bound_ctrl:1
	v_fmac_f32_e32 v179, v178, v181
	v_add_f32_e32 v170, v170, v179
	v_exp_f32_e32 v170, v170
	v_mov_b32_dpp v179, v121 row_ror:8 row_mask:0xf bank_mask:0xf bound_ctrl:1
	v_add_f32_e32 v120, v120, v178
	v_add_f32_e32 v121, v121, v179
	v_cvt_pk_bf16_f32 v133, v170, s0
	ds_write_b16 v196, v133
	v_fma_f32 v133, v173, v153, 0
	v_fmac_f32_e32 v133, v175, v155
	v_fmac_f32_e32 v133, v177, v180
	v_mul_f32_e32 v172, s24, v126
	v_mul_f32_e32 v173, s24, v127
	v_fmac_f32_e32 v133, v179, v181
	v_exp_f32_e64 v170, -|v172|
	v_add_f32_e32 v133, v171, v133
	v_exp_f32_e64 v171, -|v173|
	v_exp_f32_e32 v133, v133
	v_add_f32_e32 v170, 1.0, v170
	v_log_f32_e32 v174, v170
	v_add_f32_e32 v170, 1.0, v171
	v_log_f32_e32 v175, v170
	v_add_f32_e32 v170, v124, v120
	v_add_f32_e32 v171, v125, v121
	v_max_f32_e64 v120, -v172, 0
	v_max_f32_e64 v121, -v173, 0
	v_add_f32_e32 v120, v120, v174
	v_add_f32_e32 v121, v121, v175
	s_nop 0
	v_fma_f32 v124, -v126, s24, -v120
	v_fma_f32 v125, -v127, s24, -v121
	v_sub_f32_e32 v120, v168, v120
	v_sub_f32_e32 v121, v169, v121
	s_nop 0
	v_mov_b32_dpp v126, v124 quad_perm:[1,0,3,2] row_mask:0xf bank_mask:0xf bound_ctrl:1
	v_mov_b32_dpp v127, v125 quad_perm:[1,0,3,2] row_mask:0xf bank_mask:0xf bound_ctrl:1
	v_add_f32_e32 v124, v124, v126
	v_add_f32_e32 v125, v125, v127
	v_fma_f32 v177, v126, v153, 0
	v_cvt_pk_bf16_f32 v126, v133, s0
	v_mov_b32_dpp v172, v124 quad_perm:[2,3,0,1] row_mask:0xf bank_mask:0xf bound_ctrl:1
	v_mov_b32_dpp v173, v125 quad_perm:[2,3,0,1] row_mask:0xf bank_mask:0xf bound_ctrl:1
	v_add_f32_e32 v124, v124, v172
	v_add_f32_e32 v125, v125, v173
	v_fmac_f32_e32 v177, v172, v155
	ds_write_b16 v196, v126 offset:144
	v_mov_b32_dpp v174, v124 row_half_mirror row_mask:0xf bank_mask:0xf bound_ctrl:1
	v_mov_b32_dpp v175, v125 row_half_mirror row_mask:0xf bank_mask:0xf bound_ctrl:1
	v_add_f32_e32 v124, v124, v174
	v_add_f32_e32 v125, v125, v175
	v_fmac_f32_e32 v177, v174, v180
	s_nop 0
	v_mov_b32_dpp v176, v124 row_ror:8 row_mask:0xf bank_mask:0xf bound_ctrl:1
	v_fmac_f32_e32 v177, v176, v181
	v_add_f32_e32 v120, v120, v177
	v_exp_f32_e32 v120, v120
	v_mov_b32_dpp v177, v125 row_ror:8 row_mask:0xf bank_mask:0xf bound_ctrl:1
	v_add_f32_e32 v124, v124, v176
	v_add_f32_e32 v125, v125, v177
	v_cvt_pk_bf16_f32 v120, v120, s0
	ds_write_b16 v196, v120 offset:320
	v_fma_f32 v120, v127, v153, 0
	v_fmac_f32_e32 v120, v173, v155
	v_fmac_f32_e32 v120, v175, v180
	v_fmac_f32_e32 v120, v177, v181
	v_add_f32_e32 v126, v121, v120
	v_mul_f32_e32 v120, s24, v122
	v_mul_f32_e32 v121, s24, v123
	v_exp_f32_e32 v133, v126
	v_exp_f32_e64 v127, -|v120|
	v_exp_f32_e64 v172, -|v121|
	v_max_f32_e64 v120, -v120, 0
	v_max_f32_e64 v121, -v121, 0
	v_add_f32_e32 v126, 1.0, v127
	v_add_f32_e32 v127, 1.0, v172
	v_log_f32_e32 v126, v126
	v_log_f32_e32 v127, v127
	v_add_f32_e32 v124, v168, v124
	v_add_f32_e32 v125, v169, v125
	v_cvt_pk_bf16_f32 v133, v133, s0
	ds_write_b16 v196, v133 offset:464
	v_add_f32_e32 v120, v120, v126
	v_add_f32_e32 v121, v121, v127
	s_nop 0
	v_fma_f32 v122, -v122, s24, -v120
	v_fma_f32 v123, -v123, s24, -v121
	v_sub_f32_e32 v120, v124, v120
	v_sub_f32_e32 v121, v125, v121
	s_nop 0
	v_mov_b32_dpp v126, v122 quad_perm:[1,0,3,2] row_mask:0xf bank_mask:0xf bound_ctrl:1
	v_mov_b32_dpp v127, v123 quad_perm:[1,0,3,2] row_mask:0xf bank_mask:0xf bound_ctrl:1
	v_add_f32_e32 v122, v122, v126
	v_add_f32_e32 v123, v123, v127
	v_fma_f32 v175, v126, v153, 0
	s_nop 0
	v_mov_b32_dpp v168, v122 quad_perm:[2,3,0,1] row_mask:0xf bank_mask:0xf bound_ctrl:1
	v_mov_b32_dpp v169, v123 quad_perm:[2,3,0,1] row_mask:0xf bank_mask:0xf bound_ctrl:1
	v_add_f32_e32 v122, v122, v168
	v_add_f32_e32 v123, v123, v169
	v_fmac_f32_e32 v175, v168, v155
	s_nop 0
	v_mov_b32_dpp v172, v122 row_half_mirror row_mask:0xf bank_mask:0xf bound_ctrl:1
	v_mov_b32_dpp v173, v123 row_half_mirror row_mask:0xf bank_mask:0xf bound_ctrl:1
	v_add_f32_e32 v122, v122, v172
	v_add_f32_e32 v123, v123, v173
	v_fmac_f32_e32 v175, v172, v180
	s_nop 0
	v_mov_b32_dpp v174, v122 row_ror:8 row_mask:0xf bank_mask:0xf bound_ctrl:1
	v_fmac_f32_e32 v175, v174, v181
	v_add_f32_e32 v120, v120, v175
	v_exp_f32_e32 v120, v120
	v_mov_b32_dpp v175, v123 row_ror:8 row_mask:0xf bank_mask:0xf bound_ctrl:1
	v_add_f32_e32 v122, v122, v174
	v_add_f32_e32 v123, v123, v175
	v_cvt_pk_bf16_f32 v120, v120, s0
	ds_write_b16 v196, v120 offset:288
	v_fma_f32 v120, v127, v153, 0
	v_fmac_f32_e32 v120, v169, v155
	v_fmac_f32_e32 v120, v173, v180
	v_fmac_f32_e32 v120, v175, v181
	v_mul_f32_e32 v126, s24, v116
	v_mul_f32_e32 v127, s24, v117
	v_add_f32_e32 v120, v121, v120
	v_exp_f32_e64 v133, -|v126|
	v_exp_f32_e64 v121, -|v127|
	v_exp_f32_e32 v169, v120
	v_add_f32_e32 v174, v124, v122
	v_add_f32_e32 v175, v125, v123
	v_add_f32_e32 v120, 1.0, v133
	v_add_f32_e32 v121, 1.0, v121
	v_log_f32_e32 v120, v120
	v_log_f32_e32 v121, v121
	v_max_f32_e64 v122, -v126, 0
	v_max_f32_e64 v123, -v127, 0
	v_add_f32_e32 v120, v122, v120
	v_add_f32_e32 v121, v123, v121
	s_nop 0
	v_fma_f32 v116, -v116, s24, -v120
	v_fma_f32 v117, -v117, s24, -v121
	v_sub_f32_e32 v120, v166, v120
	v_sub_f32_e32 v121, v167, v121
	s_nop 0
	v_mov_b32_dpp v122, v116 quad_perm:[1,0,3,2] row_mask:0xf bank_mask:0xf bound_ctrl:1
	v_mov_b32_dpp v123, v117 quad_perm:[1,0,3,2] row_mask:0xf bank_mask:0xf bound_ctrl:1
	v_add_f32_e32 v116, v116, v122
	v_add_f32_e32 v117, v117, v123
	v_fma_f32 v133, v122, v153, 0
	v_cvt_pk_bf16_f32 v122, v169, s0
	v_mov_b32_dpp v124, v116 quad_perm:[2,3,0,1] row_mask:0xf bank_mask:0xf bound_ctrl:1
	v_mov_b32_dpp v125, v117 quad_perm:[2,3,0,1] row_mask:0xf bank_mask:0xf bound_ctrl:1
	v_add_f32_e32 v116, v116, v124
	v_add_f32_e32 v117, v117, v125
	v_fmac_f32_e32 v133, v124, v155
	ds_write_b16 v196, v122 offset:432
	v_mov_b32_dpp v126, v116 row_half_mirror row_mask:0xf bank_mask:0xf bound_ctrl:1
	v_mov_b32_dpp v127, v117 row_half_mirror row_mask:0xf bank_mask:0xf bound_ctrl:1
	v_add_f32_e32 v116, v116, v126
	v_add_f32_e32 v117, v117, v127
	v_fmac_f32_e32 v133, v126, v180
	s_nop 0
	v_mov_b32_dpp v168, v116 row_ror:8 row_mask:0xf bank_mask:0xf bound_ctrl:1
	v_fmac_f32_e32 v133, v168, v181
	v_add_f32_e32 v120, v120, v133
	v_exp_f32_e32 v120, v120
	v_mov_b32_dpp v169, v117 row_ror:8 row_mask:0xf bank_mask:0xf bound_ctrl:1
	v_add_f32_e32 v116, v116, v168
	v_add_f32_e32 v117, v117, v169
	v_cvt_pk_bf16_f32 v120, v120, s0
	ds_write_b16 v196, v120 offset:2336
	v_fma_f32 v120, v123, v153, 0
	v_fmac_f32_e32 v120, v125, v155
	v_fmac_f32_e32 v120, v127, v180
	v_fmac_f32_e32 v120, v169, v181
	v_add_f32_e32 v122, v121, v120
	v_mul_f32_e32 v120, s24, v112
	v_mul_f32_e32 v121, s24, v113
	v_exp_f32_e32 v124, v122
	v_exp_f32_e64 v123, -|v120|
	v_exp_f32_e64 v125, -|v121|
	v_max_f32_e64 v120, -v120, 0
	v_max_f32_e64 v121, -v121, 0
	v_add_f32_e32 v122, 1.0, v123
	v_add_f32_e32 v123, 1.0, v125
	v_log_f32_e32 v122, v122
	v_log_f32_e32 v123, v123
	v_cvt_pk_bf16_f32 v133, v124, s0
	v_add_f32_e32 v116, v166, v116
	v_add_f32_e32 v117, v167, v117
	ds_write_b16 v196, v133 offset:2480
	v_add_f32_e32 v120, v120, v122
	v_add_f32_e32 v121, v121, v123
	s_nop 0
	v_fma_f32 v112, -v112, s24, -v120
	v_fma_f32 v113, -v113, s24, -v121
	v_sub_f32_e32 v120, v116, v120
	v_sub_f32_e32 v121, v117, v121
	s_nop 0
	v_mov_b32_dpp v122, v112 quad_perm:[1,0,3,2] row_mask:0xf bank_mask:0xf bound_ctrl:1
	v_mov_b32_dpp v123, v113 quad_perm:[1,0,3,2] row_mask:0xf bank_mask:0xf bound_ctrl:1
	v_add_f32_e32 v112, v112, v122
	v_add_f32_e32 v113, v113, v123
	v_fma_f32 v167, v122, v153, 0
	s_nop 0
	v_mov_b32_dpp v124, v112 quad_perm:[2,3,0,1] row_mask:0xf bank_mask:0xf bound_ctrl:1
	v_mov_b32_dpp v125, v113 quad_perm:[2,3,0,1] row_mask:0xf bank_mask:0xf bound_ctrl:1
	v_add_f32_e32 v112, v112, v124
	v_add_f32_e32 v113, v113, v125
	v_fmac_f32_e32 v167, v124, v155
	s_nop 0
	v_mov_b32_dpp v126, v112 row_half_mirror row_mask:0xf bank_mask:0xf bound_ctrl:1
	v_mov_b32_dpp v127, v113 row_half_mirror row_mask:0xf bank_mask:0xf bound_ctrl:1
	v_add_f32_e32 v112, v112, v126
	v_add_f32_e32 v113, v113, v127
	v_fmac_f32_e32 v167, v126, v180
	s_nop 0
	v_mov_b32_dpp v166, v112 row_ror:8 row_mask:0xf bank_mask:0xf bound_ctrl:1
	v_fmac_f32_e32 v167, v166, v181
	v_add_f32_e32 v120, v120, v167
	v_exp_f32_e32 v120, v120
	v_mov_b32_dpp v167, v113 row_ror:8 row_mask:0xf bank_mask:0xf bound_ctrl:1
	v_add_f32_e32 v112, v112, v166
	v_add_f32_e32 v113, v113, v167
	v_cvt_pk_bf16_f32 v120, v120, s0
	ds_write_b16 v196, v120 offset:2304
	v_fma_f32 v120, v123, v153, 0
	v_fmac_f32_e32 v120, v125, v155
	v_fmac_f32_e32 v120, v127, v180
	v_fmac_f32_e32 v120, v167, v181
	v_mul_f32_e32 v122, s24, v118
	v_mul_f32_e32 v123, s24, v119
	v_add_f32_e32 v120, v121, v120
	v_exp_f32_e64 v124, -|v122|
	v_exp_f32_e64 v121, -|v123|
	v_exp_f32_e32 v125, v120
	v_add_f32_e32 v176, v116, v112
	v_add_f32_e32 v177, v117, v113
	v_add_f32_e32 v120, 1.0, v124
	v_add_f32_e32 v121, 1.0, v121
	v_log_f32_e32 v120, v120
	v_log_f32_e32 v121, v121
	v_max_f32_e64 v112, -v122, 0
	v_max_f32_e64 v113, -v123, 0
	v_add_f32_e32 v112, v112, v120
	v_add_f32_e32 v113, v113, v121
	s_nop 0
	v_fma_f32 v116, -v118, s24, -v112
	v_fma_f32 v117, -v119, s24, -v113
	v_sub_f32_e32 v112, v164, v112
	v_sub_f32_e32 v113, v165, v113
	s_nop 0
	v_mov_b32_dpp v118, v116 quad_perm:[1,0,3,2] row_mask:0xf bank_mask:0xf bound_ctrl:1
	v_mov_b32_dpp v119, v117 quad_perm:[1,0,3,2] row_mask:0xf bank_mask:0xf bound_ctrl:1
	v_add_f32_e32 v116, v116, v118
	v_add_f32_e32 v117, v117, v119
	v_fma_f32 v126, v118, v153, 0
	v_cvt_pk_bf16_f32 v118, v125, s0
	v_mov_b32_dpp v120, v116 quad_perm:[2,3,0,1] row_mask:0xf bank_mask:0xf bound_ctrl:1
	v_mov_b32_dpp v121, v117 quad_perm:[2,3,0,1] row_mask:0xf bank_mask:0xf bound_ctrl:1
	v_add_f32_e32 v116, v116, v120
	v_add_f32_e32 v117, v117, v121
	v_fmac_f32_e32 v126, v120, v155
	ds_write_b16 v196, v118 offset:2448
	v_mov_b32_dpp v122, v116 row_half_mirror row_mask:0xf bank_mask:0xf bound_ctrl:1
	v_mov_b32_dpp v123, v117 row_half_mirror row_mask:0xf bank_mask:0xf bound_ctrl:1
	v_add_f32_e32 v116, v116, v122
	v_add_f32_e32 v117, v117, v123
	v_fmac_f32_e32 v126, v122, v180
	s_nop 0
	v_mov_b32_dpp v124, v116 row_ror:8 row_mask:0xf bank_mask:0xf bound_ctrl:1
	v_fmac_f32_e32 v126, v124, v181
	v_add_f32_e32 v112, v112, v126
; __device__ void phase_attn(const Params& p, char* smem) {
;     ...
;           for (int j = 0; j < 4; ++j) rowss[m][j] += Oc[m][nn][j] * Oc[m][nn][j];
; #pragma unroll
;       for (int m = 0; m < 2; ++m)
; #pragma unroll
;         for (int nn = 0; nn < 4; ++nn) {
;           if (hh == 0) {
; #pragma unroll
;             for (int j = 0; j < 4; ++j) sO[((m * 4 + nn) * 4 + j) * 64 + lane] = Oc[m][nn][j];
;           } else {
;             O1[m][nn] = Oc[m][nn];
;           }
;         }
;     }
; #pragma unroll
;     for (int m = 0; m < 2; ++m)
; #pragma unroll
;       for (int j = 0; j < 4; ++j) {
;         const float v = row16_sum(rowss[m][j]);
;         if (l15 == 0) sSsq[w * 32 + m * 16 + lq * 4 + j] = v;
;       }
	v_exp_f32_e32 v112, v112
	v_mov_b32_dpp v125, v117 row_ror:8 row_mask:0xf bank_mask:0xf bound_ctrl:1
	v_add_f32_e32 v116, v116, v124
	v_add_f32_e32 v117, v117, v125
	v_cvt_pk_bf16_f32 v112, v112, s0
	ds_write_b16 v196, v112 offset:2624
	v_fma_f32 v112, v119, v153, 0
	v_fmac_f32_e32 v112, v121, v155
	v_fmac_f32_e32 v112, v123, v180
	v_fmac_f32_e32 v112, v125, v181
	v_add_f32_e32 v112, v113, v112
	v_exp_f32_e32 v118, v112
	v_mul_f32_e32 v112, s24, v114
	v_mul_f32_e32 v113, s24, v115
	v_add_f32_e32 v116, v164, v116
	v_add_f32_e32 v117, v165, v117
	v_exp_f32_e64 v119, -|v112|
	v_exp_f32_e64 v120, -|v113|
	v_cvt_pk_bf16_f32 v121, v118, s0
	v_max_f32_e64 v112, -v112, 0
	v_add_f32_e32 v118, 1.0, v119
	v_add_f32_e32 v119, 1.0, v120
	v_log_f32_e32 v118, v118
	v_log_f32_e32 v119, v119
	v_max_f32_e64 v113, -v113, 0
	ds_write_b16 v196, v121 offset:2768
	v_add_f32_e32 v112, v112, v118
	v_add_f32_e32 v113, v113, v119
	s_nop 0
	v_fma_f32 v114, -v114, s24, -v112
	v_fma_f32 v115, -v115, s24, -v113
	v_sub_f32_e32 v112, v116, v112
	v_sub_f32_e32 v113, v117, v113
	s_nop 0
	v_mov_b32_dpp v118, v114 quad_perm:[1,0,3,2] row_mask:0xf bank_mask:0xf bound_ctrl:1
	v_mov_b32_dpp v119, v115 quad_perm:[1,0,3,2] row_mask:0xf bank_mask:0xf bound_ctrl:1
	v_add_f32_e32 v114, v114, v118
	v_add_f32_e32 v115, v115, v119
	v_fma_f32 v126, v118, v153, 0
	v_fma_f32 v118, v119, v153, 0
	v_mov_b32_dpp v120, v114 quad_perm:[2,3,0,1] row_mask:0xf bank_mask:0xf bound_ctrl:1
	v_mov_b32_dpp v121, v115 quad_perm:[2,3,0,1] row_mask:0xf bank_mask:0xf bound_ctrl:1
	v_add_f32_e32 v114, v114, v120
	v_add_f32_e32 v115, v115, v121
	v_fmac_f32_e32 v126, v120, v155
	v_fmac_f32_e32 v118, v121, v155
	v_mov_b32_dpp v122, v114 row_half_mirror row_mask:0xf bank_mask:0xf bound_ctrl:1
	v_mov_b32_dpp v123, v115 row_half_mirror row_mask:0xf bank_mask:0xf bound_ctrl:1
	v_add_f32_e32 v114, v114, v122
	v_add_f32_e32 v115, v115, v123
	v_fmac_f32_e32 v126, v122, v180
	v_fmac_f32_e32 v118, v123, v180
	v_mov_b32_dpp v124, v114 row_ror:8 row_mask:0xf bank_mask:0xf bound_ctrl:1
	v_mov_b32_dpp v125, v115 row_ror:8 row_mask:0xf bank_mask:0xf bound_ctrl:1
	v_fmac_f32_e32 v126, v124, v181
	v_fmac_f32_e32 v118, v125, v181
	v_add_f32_e32 v112, v112, v126
	v_add_f32_e32 v113, v113, v118
	v_exp_f32_e32 v112, v112
	v_exp_f32_e32 v113, v113
	v_add_f32_e32 v114, v114, v124
	v_add_f32_e32 v115, v115, v125
	v_cvt_pk_bf16_f32 v112, v112, s0
	v_add_f32_e32 v178, v116, v114
	v_add_f32_e32 v179, v117, v115
	v_cvt_pk_bf16_f32 v133, v113, s0
	ds_write_b16 v196, v112 offset:2592
	s_branch .LBB0_230
.LBB0_235:
	v_mul_f32_e32 v20, v20, v20
	v_fmac_f32_e32 v20, v16, v16
	v_fmac_f32_e32 v20, v24, v24
	v_fmac_f32_e32 v20, v28, v28
	v_fmac_f32_e32 v20, v48, v48
	v_fmac_f32_e32 v20, v52, v52
	v_fmac_f32_e32 v20, v56, v56
	v_fmac_f32_e32 v20, v60, v60
	s_nop 1
	v_add_f32_dpp v16, v20, v20 quad_perm:[1,0,3,2] row_mask:0xf bank_mask:0xf bound_ctrl:1
	s_nop 1
	v_add_f32_dpp v16, v16, v16 quad_perm:[2,3,0,1] row_mask:0xf bank_mask:0xf bound_ctrl:1
	s_nop 1
	v_add_f32_dpp v20, v16, v16 row_half_mirror row_mask:0xf bank_mask:0xf bound_ctrl:1
	v_add_u32_e32 v16, v128, v130
	s_nop 0
	v_mov_b32_dpp v24, v20 row_ror:8 row_mask:0xf bank_mask:0xf bound_ctrl:1
	s_and_saveexec_b64 s[6:7], s[4:5]
	v_add_f32_e32 v20, v20, v24
	ds_write_b32 v16, v20 offset:18432
	s_or_b64 exec, exec, s[6:7]
	v_mul_f32_e32 v20, v21, v21
	v_fmac_f32_e32 v20, v17, v17
	v_fmac_f32_e32 v20, v25, v25
	v_fmac_f32_e32 v20, v29, v29
	v_fmac_f32_e32 v20, v49, v49
	v_fmac_f32_e32 v20, v53, v53
	v_fmac_f32_e32 v20, v57, v57
	v_fmac_f32_e32 v20, v61, v61
	s_nop 1
	v_add_f32_dpp v17, v20, v20 quad_perm:[1,0,3,2] row_mask:0xf bank_mask:0xf bound_ctrl:1
	s_nop 1
	v_add_f32_dpp v17, v17, v17 quad_perm:[2,3,0,1] row_mask:0xf bank_mask:0xf bound_ctrl:1
	s_nop 1
	v_add_f32_dpp v17, v17, v17 row_half_mirror row_mask:0xf bank_mask:0xf bound_ctrl:1
	s_nop 1
	v_mov_b32_dpp v20, v17 row_ror:8 row_mask:0xf bank_mask:0xf bound_ctrl:1
	s_and_saveexec_b64 s[6:7], s[4:5]
	v_add_f32_e32 v17, v17, v20
	ds_write_b32 v16, v17 offset:18436
	s_or_b64 exec, exec, s[6:7]
	v_mul_f32_e32 v17, v22, v22
	v_fmac_f32_e32 v17, v18, v18
	v_fmac_f32_e32 v17, v26, v26
	v_fmac_f32_e32 v17, v30, v30
	v_fmac_f32_e32 v17, v50, v50
	v_fmac_f32_e32 v17, v54, v54
	v_fmac_f32_e32 v17, v58, v58
	v_fmac_f32_e32 v17, v62, v62
	s_nop 1
	v_add_f32_dpp v17, v17, v17 quad_perm:[1,0,3,2] row_mask:0xf bank_mask:0xf bound_ctrl:1
	s_nop 1
	v_add_f32_dpp v17, v17, v17 quad_perm:[2,3,0,1] row_mask:0xf bank_mask:0xf bound_ctrl:1
	s_nop 1
	v_add_f32_dpp v17, v17, v17 row_half_mirror row_mask:0xf bank_mask:0xf bound_ctrl:1
	s_nop 1
	v_mov_b32_dpp v18, v17 row_ror:8 row_mask:0xf bank_mask:0xf bound_ctrl:1
	s_and_saveexec_b64 s[6:7], s[4:5]
	v_add_f32_e32 v17, v17, v18
	ds_write_b32 v16, v17 offset:18440
	s_or_b64 exec, exec, s[6:7]
	v_mul_f32_e32 v17, v23, v23
	v_fmac_f32_e32 v17, v19, v19
	v_fmac_f32_e32 v17, v27, v27
	v_fmac_f32_e32 v17, v31, v31
	v_fmac_f32_e32 v17, v51, v51
	v_fmac_f32_e32 v17, v55, v55
	v_fmac_f32_e32 v17, v59, v59
	v_fmac_f32_e32 v17, v63, v63
	s_nop 1
	v_add_f32_dpp v17, v17, v17 quad_perm:[1,0,3,2] row_mask:0xf bank_mask:0xf bound_ctrl:1
	s_nop 1
	v_add_f32_dpp v17, v17, v17 quad_perm:[2,3,0,1] row_mask:0xf bank_mask:0xf bound_ctrl:1
	s_nop 1
	v_add_f32_dpp v17, v17, v17 row_half_mirror row_mask:0xf bank_mask:0xf bound_ctrl:1
	s_nop 1
	v_mov_b32_dpp v18, v17 row_ror:8 row_mask:0xf bank_mask:0xf bound_ctrl:1
	s_and_saveexec_b64 s[6:7], s[4:5]
	v_add_f32_e32 v17, v17, v18
	ds_write_b32 v16, v17 offset:18444
	s_or_b64 exec, exec, s[6:7]
	v_mul_f32_e32 v4, v4, v4
	v_fmac_f32_e32 v4, v0, v0
	v_fmac_f32_e32 v4, v8, v8
; __device__ void phase_attn(const Params& p, char* smem) {
;     ...
;     for (int m = 0; m < 2; ++m)
; #pragma unroll
;       for (int j = 0; j < 4; ++j) {
;         const float v = row16_sum(rowss[m][j]);
;         if (l15 == 0) sSsq[w * 32 + m * 16 + lq * 4 + j] = v;
;       }
;     __syncthreads();
; #pragma unroll
;     for (int m = 0; m < 2; ++m)
; #pragma unroll
;       for (int j = 0; j < 4; ++j) {
;         const int row = m * 16 + lq * 4 + j;
;         const float tot = sSsq[row] + sSsq[32 + row] + sSsq[64 + row] + sSsq[96 + row];
;         const float rr = rsqrtf(tot * (1.f / 512.f) + EPS);
; #pragma unroll
;         for (int hh = 0; hh < 2; ++hh)
; #pragma unroll
;           for (int nn = 0; nn < 4; ++nn)
;             mixed[(size_t)(tok0 + row) * 1024 + (w * 2 + hh) * 64 + nn * 16 + l15] =
;                 f2bf((hh == 0 ? sO[((m * 4 + nn) * 4 + j) * 64 + lane] : O1[m][nn][j]) * rr);
;       }
	v_fmac_f32_e32 v4, v12, v12
	v_fmac_f32_e32 v4, v32, v32
	v_fmac_f32_e32 v4, v36, v36
	v_fmac_f32_e32 v4, v40, v40
	v_fmac_f32_e32 v4, v44, v44
	s_nop 1
	v_add_f32_dpp v0, v4, v4 quad_perm:[1,0,3,2] row_mask:0xf bank_mask:0xf bound_ctrl:1
	s_nop 1
	v_add_f32_dpp v0, v0, v0 quad_perm:[2,3,0,1] row_mask:0xf bank_mask:0xf bound_ctrl:1
	s_nop 1
	v_add_f32_dpp v0, v0, v0 row_half_mirror row_mask:0xf bank_mask:0xf bound_ctrl:1
	s_nop 1
	v_mov_b32_dpp v4, v0 row_ror:8 row_mask:0xf bank_mask:0xf bound_ctrl:1
	s_and_saveexec_b64 s[6:7], s[4:5]
	v_add_f32_e32 v0, v0, v4
	ds_write_b32 v16, v0 offset:18496
	s_or_b64 exec, exec, s[6:7]
	v_mul_f32_e32 v0, v5, v5
	v_fmac_f32_e32 v0, v1, v1
	v_fmac_f32_e32 v0, v9, v9
	v_fmac_f32_e32 v0, v13, v13
	v_fmac_f32_e32 v0, v33, v33
	v_fmac_f32_e32 v0, v37, v37
	v_fmac_f32_e32 v0, v41, v41
	v_fmac_f32_e32 v0, v45, v45
	s_nop 1
	v_add_f32_dpp v0, v0, v0 quad_perm:[1,0,3,2] row_mask:0xf bank_mask:0xf bound_ctrl:1
	s_nop 1
	v_add_f32_dpp v0, v0, v0 quad_perm:[2,3,0,1] row_mask:0xf bank_mask:0xf bound_ctrl:1
	s_nop 1
	v_add_f32_dpp v0, v0, v0 row_half_mirror row_mask:0xf bank_mask:0xf bound_ctrl:1
	s_nop 1
	v_mov_b32_dpp v1, v0 row_ror:8 row_mask:0xf bank_mask:0xf bound_ctrl:1
	s_and_saveexec_b64 s[6:7], s[4:5]
	v_add_f32_e32 v0, v0, v1
	ds_write_b32 v16, v0 offset:18500
	s_or_b64 exec, exec, s[6:7]
	v_mul_f32_e32 v0, v6, v6
	v_fmac_f32_e32 v0, v2, v2
	v_fmac_f32_e32 v0, v10, v10
	v_fmac_f32_e32 v0, v14, v14
	v_fmac_f32_e32 v0, v34, v34
	v_fmac_f32_e32 v0, v38, v38
	v_fmac_f32_e32 v0, v42, v42
	v_fmac_f32_e32 v0, v46, v46
	s_nop 1
	v_add_f32_dpp v0, v0, v0 quad_perm:[1,0,3,2] row_mask:0xf bank_mask:0xf bound_ctrl:1
	s_nop 1
	v_add_f32_dpp v0, v0, v0 quad_perm:[2,3,0,1] row_mask:0xf bank_mask:0xf bound_ctrl:1
	s_nop 1
	v_add_f32_dpp v0, v0, v0 row_half_mirror row_mask:0xf bank_mask:0xf bound_ctrl:1
	s_nop 1
	v_mov_b32_dpp v1, v0 row_ror:8 row_mask:0xf bank_mask:0xf bound_ctrl:1
	s_and_saveexec_b64 s[6:7], s[4:5]
	v_add_f32_e32 v0, v0, v1
	ds_write_b32 v16, v0 offset:18504
	s_or_b64 exec, exec, s[6:7]
	v_mul_f32_e32 v0, v7, v7
	v_fmac_f32_e32 v0, v3, v3
	v_fmac_f32_e32 v0, v11, v11
	v_fmac_f32_e32 v0, v15, v15
	v_fmac_f32_e32 v0, v35, v35
	v_fmac_f32_e32 v0, v39, v39
	v_fmac_f32_e32 v0, v43, v43
	v_fmac_f32_e32 v0, v47, v47
	s_nop 1
	v_add_f32_dpp v0, v0, v0 quad_perm:[1,0,3,2] row_mask:0xf bank_mask:0xf bound_ctrl:1
	s_nop 1
	v_add_f32_dpp v0, v0, v0 quad_perm:[2,3,0,1] row_mask:0xf bank_mask:0xf bound_ctrl:1
	s_nop 1
	v_add_f32_dpp v0, v0, v0 row_half_mirror row_mask:0xf bank_mask:0xf bound_ctrl:1
	s_nop 1
	v_mov_b32_dpp v1, v0 row_ror:8 row_mask:0xf bank_mask:0xf bound_ctrl:1
	s_and_saveexec_b64 s[6:7], s[4:5]
	v_add_f32_e32 v0, v0, v1
	ds_write_b32 v16, v0 offset:18508
	s_or_b64 exec, exec, s[6:7]
	v_or_b32_e32 v0, s69, v182
	v_ashrrev_i32_e32 v1, 31, v0
	s_waitcnt lgkmcnt(0)
	s_barrier
	v_lshlrev_b64 v[30:31], 11, v[0:1]
	ds_read_b128 v[14:17], v130 offset:18432
	ds_read_b128 v[18:21], v130 offset:18560
	ds_read_b128 v[22:25], v130 offset:18688
	ds_read_b128 v[26:29], v130 offset:18816
	ds_read_b128 v[0:3], v130 offset:18496
	ds_read_b128 v[4:7], v130 offset:18624
	s_waitcnt lgkmcnt(4)
	v_add_f32_e32 v12, v14, v18
	v_add_f32_e32 v13, v15, v19
	ds_read_b128 v[8:11], v130 offset:18752
	s_waitcnt lgkmcnt(4)
	v_add_f32_e32 v18, v12, v22
	v_add_f32_e32 v19, v13, v23
	ds_read_b128 v[12:15], v130 offset:18880
	s_waitcnt lgkmcnt(4)
	v_add_f32_e32 v22, v18, v26
	v_add_f32_e32 v23, v19, v27
	v_mov_b64_e32 v[18:19], s[40:41]
	v_fma_f32 v22, v22, s38, v18
	v_fma_f32 v23, v23, s38, v18
	v_add_f32_e32 v16, v16, v20
	v_add_f32_e32 v17, v17, v21
	v_mul_f32_e32 v26, 0x4b800000, v22
	v_cmp_gt_f32_e32 vcc, s47, v22
	v_add_f32_e32 v16, v16, v24
	v_add_f32_e32 v17, v17, v25
	s_waitcnt lgkmcnt(2)
	v_add_f32_e32 v0, v0, v4
	v_add_f32_e32 v1, v1, v5
	v_cndmask_b32_e32 v22, v22, v26, vcc
	v_rsq_f32_e32 v22, v22
	v_lshl_add_u64 v[26:27], v[144:145], 0, v[30:31]
	ds_read2st64_b32 v[30:31], v184 offset0:80 offset1:81
	ds_read2st64_b32 v[64:65], v184 offset0:88 offset1:89
	v_add_f32_e32 v16, v16, v28
	v_add_f32_e32 v17, v17, v29
	v_mul_f32_e32 v66, 0x45800000, v22
	v_cndmask_b32_e32 v22, v22, v66, vcc
	ds_read2st64_b32 v[66:67], v184 offset0:84 offset1:85
	ds_read2st64_b32 v[68:69], v184 offset0:86 offset1:87
	ds_read2st64_b32 v[70:71], v184 offset0:82 offset1:83
	s_waitcnt lgkmcnt(4)
	v_mul_f32_e32 v30, v30, v22
	v_bfe_u32 v72, v30, 16, 1
	v_add3_u32 v30, v30, v72, s52
	global_store_short_d16_hi v[26:27], v30, off
	s_waitcnt lgkmcnt(2)
	v_mul_f32_e32 v30, v66, v22
	v_bfe_u32 v66, v30, 16, 1
	v_add3_u32 v30, v30, v66, s52
	global_store_short_d16_hi v[26:27], v30, off offset:32
	ds_read2st64_b32 v[72:73], v184 offset0:92 offset1:93
	ds_read2st64_b32 v[74:75], v184 offset0:94 offset1:95
	ds_read2st64_b32 v[76:77], v184 offset0:90 offset1:91
	v_mul_f32_e32 v30, v64, v22
	v_bfe_u32 v64, v30, 16, 1
	v_add3_u32 v30, v30, v64, s52
	global_store_short_d16_hi v[26:27], v30, off offset:64
	s_waitcnt lgkmcnt(2)
; __device__ void phase_attn(const Params& p, char* smem) {
;     ...
; #pragma unroll
;     for (int m = 0; m < 2; ++m)
; #pragma unroll
;       for (int j = 0; j < 4; ++j) {
;         const int row = m * 16 + lq * 4 + j;
;         const float tot = sSsq[row] + sSsq[32 + row] + sSsq[64 + row] + sSsq[96 + row];
;         const float rr = rsqrtf(tot * (1.f / 512.f) + EPS);
; #pragma unroll
;         for (int hh = 0; hh < 2; ++hh)
; #pragma unroll
;           for (int nn = 0; nn < 4; ++nn)
;             mixed[(size_t)(tok0 + row) * 1024 + (w * 2 + hh) * 64 + nn * 16 + l15] =
;                 f2bf((hh == 0 ? sO[((m * 4 + nn) * 4 + j) * 64 + lane] : O1[m][nn][j]) * rr);
;       }
	v_mul_f32_e32 v30, v72, v22
	v_bfe_u32 v64, v30, 16, 1
	v_add3_u32 v30, v30, v64, s52
	global_store_short_d16_hi v[26:27], v30, off offset:96
	v_mul_f32_e32 v30, v48, v22
	v_bfe_u32 v48, v30, 16, 1
	v_add3_u32 v30, v30, v48, s52
	global_store_short_d16_hi v[26:27], v30, off offset:128
	v_mul_f32_e32 v30, v52, v22
	v_bfe_u32 v48, v30, 16, 1
	v_add3_u32 v30, v30, v48, s52
	global_store_short_d16_hi v[26:27], v30, off offset:160
	v_mul_f32_e32 v30, v56, v22
	v_bfe_u32 v48, v30, 16, 1
	v_add3_u32 v30, v30, v48, s52
	global_store_short_d16_hi v[26:27], v30, off offset:192
	v_mul_f32_e32 v30, 0x4b800000, v23
	v_cmp_gt_f32_e32 vcc, s47, v23
	v_mul_f32_e32 v22, v60, v22
	v_fma_f32 v16, v16, s38, v18
	v_fma_f32 v17, v17, s38, v18
	v_cndmask_b32_e32 v23, v23, v30, vcc
	v_rsq_f32_e32 v23, v23
	v_bfe_u32 v30, v22, 16, 1
	v_add3_u32 v22, v22, v30, s52
	global_store_short_d16_hi v[26:27], v22, off offset:224
	v_mul_f32_e32 v22, 0x45800000, v23
	v_cndmask_b32_e32 v26, v23, v22, vcc
	v_or_b32_e32 v22, s69, v187
	v_ashrrev_i32_e32 v23, 31, v22
	v_mul_f32_e32 v27, v31, v26
	v_lshlrev_b64 v[22:23], 11, v[22:23]
	v_bfe_u32 v30, v27, 16, 1
	v_lshl_add_u64 v[22:23], v[144:145], 0, v[22:23]
	v_add3_u32 v27, v27, v30, s52
	global_store_short_d16_hi v[22:23], v27, off
	v_mul_f32_e32 v27, v67, v26
	v_bfe_u32 v30, v27, 16, 1
	v_add3_u32 v27, v27, v30, s52
	global_store_short_d16_hi v[22:23], v27, off offset:32
	v_mul_f32_e32 v27, v65, v26
	v_bfe_u32 v30, v27, 16, 1
	v_add3_u32 v27, v27, v30, s52
	global_store_short_d16_hi v[22:23], v27, off offset:64
	v_mul_f32_e32 v27, v73, v26
	v_bfe_u32 v30, v27, 16, 1
	v_add3_u32 v27, v27, v30, s52
	global_store_short_d16_hi v[22:23], v27, off offset:96
	v_mul_f32_e32 v27, v49, v26
	v_bfe_u32 v30, v27, 16, 1
	v_add3_u32 v27, v27, v30, s52
	global_store_short_d16_hi v[22:23], v27, off offset:128
	v_mul_f32_e32 v27, v53, v26
	v_bfe_u32 v30, v27, 16, 1
	v_add3_u32 v27, v27, v30, s52
	global_store_short_d16_hi v[22:23], v27, off offset:160
	v_mul_f32_e32 v27, v57, v26
	v_bfe_u32 v30, v27, 16, 1
	v_mul_f32_e32 v20, 0x4b800000, v16
	v_cmp_gt_f32_e32 vcc, s47, v16
	v_add3_u32 v27, v27, v30, s52
	v_mul_f32_e32 v26, v61, v26
	v_cndmask_b32_e32 v16, v16, v20, vcc
	global_store_short_d16_hi v[22:23], v27, off offset:192
	v_bfe_u32 v27, v26, 16, 1
	v_rsq_f32_e32 v16, v16
	v_add3_u32 v26, v26, v27, s52
	global_store_short_d16_hi v[22:23], v26, off offset:224
	v_or_b32_e32 v22, s69, v188
	v_ashrrev_i32_e32 v23, 31, v22
	v_lshlrev_b64 v[20:21], 11, v[22:23]
	v_mul_f32_e32 v22, 0x45800000, v16
	v_cndmask_b32_e32 v16, v16, v22, vcc
	v_mul_f32_e32 v22, v70, v16
	v_bfe_u32 v23, v22, 16, 1
	v_lshl_add_u64 v[20:21], v[144:145], 0, v[20:21]
	v_add3_u32 v22, v22, v23, s52
	global_store_short_d16_hi v[20:21], v22, off
	v_mul_f32_e32 v22, v68, v16
	v_bfe_u32 v23, v22, 16, 1
	v_add3_u32 v22, v22, v23, s52
	global_store_short_d16_hi v[20:21], v22, off offset:32
	s_waitcnt lgkmcnt(0)
	v_mul_f32_e32 v22, v76, v16
	v_bfe_u32 v23, v22, 16, 1
	v_add3_u32 v22, v22, v23, s52
	global_store_short_d16_hi v[20:21], v22, off offset:64
	v_mul_f32_e32 v22, v74, v16
	v_bfe_u32 v23, v22, 16, 1
	v_add3_u32 v22, v22, v23, s52
	global_store_short_d16_hi v[20:21], v22, off offset:96
	v_mul_f32_e32 v22, v50, v16
	v_bfe_u32 v23, v22, 16, 1
	v_add3_u32 v22, v22, v23, s52
	global_store_short_d16_hi v[20:21], v22, off offset:128
	v_mul_f32_e32 v22, v54, v16
	v_bfe_u32 v23, v22, 16, 1
	v_add3_u32 v22, v22, v23, s52
	global_store_short_d16_hi v[20:21], v22, off offset:160
	v_mul_f32_e32 v22, v58, v16
	v_bfe_u32 v23, v22, 16, 1
	v_add3_u32 v22, v22, v23, s52
	global_store_short_d16_hi v[20:21], v22, off offset:192
	v_mul_f32_e32 v22, 0x4b800000, v17
	v_cmp_gt_f32_e32 vcc, s47, v17
	v_mul_f32_e32 v16, v62, v16
	v_add_f32_e32 v0, v0, v8
	v_add_f32_e32 v1, v1, v9
	v_cndmask_b32_e32 v17, v17, v22, vcc
	v_rsq_f32_e32 v17, v17
	v_bfe_u32 v22, v16, 16, 1
	v_add3_u32 v16, v16, v22, s52
	global_store_short_d16_hi v[20:21], v16, off offset:224
	v_mul_f32_e32 v16, 0x45800000, v17
	v_cndmask_b32_e32 v20, v17, v16, vcc
	v_or_b32_e32 v16, s69, v189
	v_ashrrev_i32_e32 v17, 31, v16
	v_mul_f32_e32 v21, v71, v20
	v_lshlrev_b64 v[16:17], 11, v[16:17]
	v_bfe_u32 v22, v21, 16, 1
	v_lshl_add_u64 v[16:17], v[144:145], 0, v[16:17]
	v_add3_u32 v21, v21, v22, s52
	global_store_short_d16_hi v[16:17], v21, off
	v_mul_f32_e32 v21, v69, v20
	v_bfe_u32 v22, v21, 16, 1
	v_add3_u32 v21, v21, v22, s52
	global_store_short_d16_hi v[16:17], v21, off offset:32
	v_mul_f32_e32 v21, v77, v20
	v_bfe_u32 v22, v21, 16, 1
	v_add3_u32 v21, v21, v22, s52
	global_store_short_d16_hi v[16:17], v21, off offset:64
	v_mul_f32_e32 v21, v75, v20
	v_bfe_u32 v22, v21, 16, 1
	v_add3_u32 v21, v21, v22, s52
	global_store_short_d16_hi v[16:17], v21, off offset:96
	v_mul_f32_e32 v21, v51, v20
	v_bfe_u32 v22, v21, 16, 1
	v_add3_u32 v21, v21, v22, s52
	global_store_short_d16_hi v[16:17], v21, off offset:128
	v_mul_f32_e32 v21, v55, v20
	v_bfe_u32 v22, v21, 16, 1
	v_add3_u32 v21, v21, v22, s52
	global_store_short_d16_hi v[16:17], v21, off offset:160
	v_mul_f32_e32 v21, v59, v20
	v_add_f32_e32 v0, v0, v12
	v_add_f32_e32 v1, v1, v13
	v_bfe_u32 v22, v21, 16, 1
	v_fma_f32 v0, v0, s38, v18
	v_fma_f32 v1, v1, s38, v18
	v_add3_u32 v21, v21, v22, s52
	v_mul_f32_e32 v20, v63, v20
	v_mul_f32_e32 v4, 0x4b800000, v0
	v_cmp_gt_f32_e32 vcc, s47, v0
	global_store_short_d16_hi v[16:17], v21, off offset:192
	v_bfe_u32 v21, v20, 16, 1
	v_cndmask_b32_e32 v0, v0, v4, vcc
	v_add3_u32 v20, v20, v21, s52
	v_rsq_f32_e32 v0, v0
	global_store_short_d16_hi v[16:17], v20, off offset:224
	v_or_b32_e32 v16, s69, v190
	v_ashrrev_i32_e32 v17, 31, v16
	ds_read2st64_b32 v[8:9], v184 offset0:96 offset1:97
	ds_read2st64_b32 v[12:13], v184 offset0:104 offset1:105
	v_lshlrev_b64 v[16:17], 11, v[16:17]
	v_lshl_add_u64 v[4:5], v[144:145], 0, v[16:17]
	v_mul_f32_e32 v16, 0x45800000, v0
	v_cndmask_b32_e32 v0, v0, v16, vcc
	ds_read2st64_b32 v[16:17], v184 offset0:100 offset1:101
	ds_read2st64_b32 v[20:21], v184 offset0:102 offset1:103
	ds_read2st64_b32 v[22:23], v184 offset0:98 offset1:99
	s_waitcnt lgkmcnt(4)
; __device__ void phase_attn(const Params& p, char* smem) {
;     ...
; #pragma unroll
;     for (int m = 0; m < 2; ++m)
; #pragma unroll
;       for (int j = 0; j < 4; ++j) {
;         const int row = m * 16 + lq * 4 + j;
;         const float tot = sSsq[row] + sSsq[32 + row] + sSsq[64 + row] + sSsq[96 + row];
;         const float rr = rsqrtf(tot * (1.f / 512.f) + EPS);
; #pragma unroll
;         for (int hh = 0; hh < 2; ++hh)
; #pragma unroll
;           for (int nn = 0; nn < 4; ++nn)
;             mixed[(size_t)(tok0 + row) * 1024 + (w * 2 + hh) * 64 + nn * 16 + l15] =
;                 f2bf((hh == 0 ? sO[((m * 4 + nn) * 4 + j) * 64 + lane] : O1[m][nn][j]) * rr);
;       }
	v_mul_f32_e32 v8, v8, v0
	v_bfe_u32 v24, v8, 16, 1
	v_add3_u32 v8, v8, v24, s52
	global_store_short_d16_hi v[4:5], v8, off
	s_waitcnt lgkmcnt(2)
	v_mul_f32_e32 v8, v16, v0
	v_bfe_u32 v16, v8, 16, 1
	v_add3_u32 v8, v8, v16, s52
	global_store_short_d16_hi v[4:5], v8, off offset:32
	ds_read2st64_b32 v[24:25], v184 offset0:108 offset1:109
	ds_read2st64_b32 v[26:27], v184 offset0:110 offset1:111
	ds_read2st64_b32 v[28:29], v184 offset0:106 offset1:107
	v_mul_f32_e32 v8, v12, v0
	v_bfe_u32 v12, v8, 16, 1
	v_add3_u32 v8, v8, v12, s52
	global_store_short_d16_hi v[4:5], v8, off offset:64
	s_waitcnt lgkmcnt(2)
	v_mul_f32_e32 v8, v24, v0
	v_bfe_u32 v12, v8, 16, 1
	v_add3_u32 v8, v8, v12, s52
	global_store_short_d16_hi v[4:5], v8, off offset:96
	v_mul_f32_e32 v8, v32, v0
	v_bfe_u32 v12, v8, 16, 1
	v_add3_u32 v8, v8, v12, s52
	global_store_short_d16_hi v[4:5], v8, off offset:128
	v_mul_f32_e32 v8, v36, v0
	v_bfe_u32 v12, v8, 16, 1
	v_add3_u32 v8, v8, v12, s52
	global_store_short_d16_hi v[4:5], v8, off offset:160
	v_mul_f32_e32 v8, v40, v0
	v_bfe_u32 v12, v8, 16, 1
	v_add3_u32 v8, v8, v12, s52
	global_store_short_d16_hi v[4:5], v8, off offset:192
	v_mul_f32_e32 v8, 0x4b800000, v1
	v_cmp_gt_f32_e32 vcc, s47, v1
	v_mul_f32_e32 v0, v44, v0
	v_add_f32_e32 v2, v2, v6
	v_add_f32_e32 v3, v3, v7
	v_cndmask_b32_e32 v1, v1, v8, vcc
	v_rsq_f32_e32 v1, v1
	v_bfe_u32 v8, v0, 16, 1
	v_add3_u32 v0, v0, v8, s52
	global_store_short_d16_hi v[4:5], v0, off offset:224
	v_mul_f32_e32 v0, 0x45800000, v1
	v_cndmask_b32_e32 v4, v1, v0, vcc
	v_or_b32_e32 v0, s69, v191
	v_ashrrev_i32_e32 v1, 31, v0
	v_mul_f32_e32 v5, v9, v4
	v_lshlrev_b64 v[0:1], 11, v[0:1]
	v_bfe_u32 v8, v5, 16, 1
	v_lshl_add_u64 v[0:1], v[144:145], 0, v[0:1]
	v_add3_u32 v5, v5, v8, s52
	global_store_short_d16_hi v[0:1], v5, off
	v_mul_f32_e32 v5, v17, v4
	v_bfe_u32 v8, v5, 16, 1
	v_add3_u32 v5, v5, v8, s52
	global_store_short_d16_hi v[0:1], v5, off offset:32
	v_mul_f32_e32 v5, v13, v4
	v_bfe_u32 v8, v5, 16, 1
	v_add3_u32 v5, v5, v8, s52
	global_store_short_d16_hi v[0:1], v5, off offset:64
	v_mul_f32_e32 v5, v25, v4
	v_bfe_u32 v8, v5, 16, 1
	v_add3_u32 v5, v5, v8, s52
	global_store_short_d16_hi v[0:1], v5, off offset:96
	v_mul_f32_e32 v5, v33, v4
	v_bfe_u32 v8, v5, 16, 1
	v_add3_u32 v5, v5, v8, s52
	global_store_short_d16_hi v[0:1], v5, off offset:128
	v_mul_f32_e32 v5, v37, v4
	v_bfe_u32 v8, v5, 16, 1
	v_add3_u32 v5, v5, v8, s52
	global_store_short_d16_hi v[0:1], v5, off offset:160
	v_mul_f32_e32 v5, v41, v4
	v_bfe_u32 v8, v5, 16, 1
	v_add3_u32 v5, v5, v8, s52
	v_mul_f32_e32 v4, v45, v4
	v_add_f32_e32 v2, v2, v10
	v_add_f32_e32 v3, v3, v11
	global_store_short_d16_hi v[0:1], v5, off offset:192
	v_bfe_u32 v5, v4, 16, 1
	v_add_f32_e32 v2, v2, v14
	v_add_f32_e32 v3, v3, v15
	v_add3_u32 v4, v4, v5, s52
	v_fma_f32 v2, v2, s38, v18
	v_fma_f32 v3, v3, s38, v18
	global_store_short_d16_hi v[0:1], v4, off offset:224
	v_mul_f32_e32 v1, 0x4b800000, v2
	v_cmp_gt_f32_e32 vcc, s47, v2
	v_or_b32_e32 v0, s69, v194
	v_and_b32_e32 v24, 64, v199
	v_cndmask_b32_e32 v1, v2, v1, vcc
	v_rsq_f32_e32 v2, v1
	v_ashrrev_i32_e32 v1, 31, v0
	v_lshlrev_b64 v[0:1], 11, v[0:1]
	v_lshl_add_u64 v[0:1], v[144:145], 0, v[0:1]
	v_mul_f32_e32 v4, 0x45800000, v2
	v_cndmask_b32_e32 v2, v2, v4, vcc
	v_mul_f32_e32 v4, v22, v2
	v_bfe_u32 v5, v4, 16, 1
	v_add3_u32 v4, v4, v5, s52
	global_store_short_d16_hi v[0:1], v4, off
	v_mul_f32_e32 v4, v20, v2
	v_bfe_u32 v5, v4, 16, 1
	v_add3_u32 v4, v4, v5, s52
	global_store_short_d16_hi v[0:1], v4, off offset:32
	s_waitcnt lgkmcnt(0)
; __device__ __forceinline__ float bflo(unsigned w) { return __uint_as_float(w << 16); }
; __device__ __forceinline__ float bfhi(unsigned w) { return __uint_as_float(w & 0xFFFF0000u); }
; __device__ void phase_attn(const Params& p, char* smem) {
;     ...
;         for (int hh = 0; hh < 2; ++hh)
; #pragma unroll
;           for (int nn = 0; nn < 4; ++nn)
;             mixed[(size_t)(tok0 + row) * 1024 + (w * 2 + hh) * 64 + nn * 16 + l15] =
;                 f2bf((hh == 0 ? sO[((m * 4 + nn) * 4 + j) * 64 + lane] : O1[m][nn][j]) * rr);
;       }
;     ...
;       const int c8 = lane * 8;
;       float w0[8], w1[8], w2[8];
; #pragma unroll
;       for (int i = 0; i < 8; ++i) {
;         w0[i] = p.conv_w[c8 + i]; w1[i] = p.conv_w[512 + c8 + i]; w2[i] = p.conv_w[1024 + c8 + i];
;       }
;       for (int i = 0; i < 8; ++i) {
;         const int pos = q0 + w * 8 + i;
;         const size_t tg = (size_t)(b * S + pos);
;         float pr[3][8];
; #pragma unroll
;         for (int d = 0; d < 3; ++d) {
;           const int pp = pos - 2 + d;
;           if (pp >= 0) {
;             const uint4 cc = *(const uint4*)(bcx + (tg - 2 + d) * 1536 + 512 + c8);
;             const uint4 xx = *(const uint4*)(bcx + (tg - 2 + d) * 1536 + 1024 + c8);
;             pr[d][0] = bflo(cc.x) * bflo(xx.x); pr[d][1] = bfhi(cc.x) * bfhi(xx.x);
;             pr[d][2] = bflo(cc.y) * bflo(xx.y); pr[d][3] = bfhi(cc.y) * bfhi(xx.y);
;             pr[d][4] = bflo(cc.z) * bflo(xx.z); pr[d][5] = bfhi(cc.z) * bfhi(xx.z);
;             pr[d][6] = bflo(cc.w) * bflo(xx.w); pr[d][7] = bfhi(cc.w) * bfhi(xx.w);
;           } else {
; #pragma unroll
;             for (int e = 0; e < 8; ++e) pr[d][e] = 0.f;
;           }
;         }
;         const uint4 bb = *(const uint4*)(bcx + tg * 1536 + c8);
;         float gb[8] = {bflo(bb.x), bfhi(bb.x), bflo(bb.y), bfhi(bb.y), bflo(bb.z), bfhi(bb.z), bflo(bb.w), bfhi(bb.w)};
	v_mul_f32_e32 v4, v28, v2
	v_bfe_u32 v5, v4, 16, 1
	v_add3_u32 v4, v4, v5, s52
	global_store_short_d16_hi v[0:1], v4, off offset:64
	v_mul_f32_e32 v4, v26, v2
	v_bfe_u32 v5, v4, 16, 1
	v_add3_u32 v4, v4, v5, s52
	global_store_short_d16_hi v[0:1], v4, off offset:96
	v_mul_f32_e32 v4, v34, v2
	v_bfe_u32 v5, v4, 16, 1
	v_add3_u32 v4, v4, v5, s52
	global_store_short_d16_hi v[0:1], v4, off offset:128
	v_mul_f32_e32 v4, v38, v2
	v_bfe_u32 v5, v4, 16, 1
	v_add3_u32 v4, v4, v5, s52
	global_store_short_d16_hi v[0:1], v4, off offset:160
	v_mul_f32_e32 v4, v42, v2
	v_bfe_u32 v5, v4, 16, 1
	v_add3_u32 v4, v4, v5, s52
	global_store_short_d16_hi v[0:1], v4, off offset:192
	v_mul_f32_e32 v4, 0x4b800000, v3
	v_cmp_gt_f32_e32 vcc, s47, v3
	v_mul_f32_e32 v2, v46, v2
	v_add_u32_e32 v24, 64, v24
	v_cndmask_b32_e32 v3, v3, v4, vcc
	v_rsq_f32_e32 v3, v3
	v_bfe_u32 v4, v2, 16, 1
	v_add3_u32 v2, v2, v4, s52
	global_store_short_d16_hi v[0:1], v2, off offset:224
	v_mul_f32_e32 v0, 0x45800000, v3
	v_cndmask_b32_e32 v2, v3, v0, vcc
	v_or_b32_e32 v0, s69, v195
	v_ashrrev_i32_e32 v1, 31, v0
	v_mul_f32_e32 v3, v23, v2
	v_lshlrev_b64 v[0:1], 11, v[0:1]
	v_bfe_u32 v4, v3, 16, 1
	v_lshl_add_u64 v[0:1], v[144:145], 0, v[0:1]
	v_add3_u32 v3, v3, v4, s52
	global_store_short_d16_hi v[0:1], v3, off
	v_mul_f32_e32 v3, v21, v2
	v_bfe_u32 v4, v3, 16, 1
	v_add3_u32 v3, v3, v4, s52
	global_store_short_d16_hi v[0:1], v3, off offset:32
	v_mul_f32_e32 v3, v29, v2
	v_bfe_u32 v4, v3, 16, 1
	v_add3_u32 v3, v3, v4, s52
	global_store_short_d16_hi v[0:1], v3, off offset:64
	v_mul_f32_e32 v3, v27, v2
	v_bfe_u32 v4, v3, 16, 1
	v_add3_u32 v3, v3, v4, s52
	global_store_short_d16_hi v[0:1], v3, off offset:96
	v_mul_f32_e32 v3, v35, v2
	v_bfe_u32 v4, v3, 16, 1
	v_add3_u32 v3, v3, v4, s52
	global_store_short_d16_hi v[0:1], v3, off offset:128
	v_mul_f32_e32 v3, v39, v2
	v_bfe_u32 v4, v3, 16, 1
	v_add3_u32 v3, v3, v4, s52
	global_store_short_d16_hi v[0:1], v3, off offset:160
	v_mul_f32_e32 v3, v43, v2
	v_bfe_u32 v4, v3, 16, 1
	v_add3_u32 v3, v3, v4, s52
	v_mul_f32_e32 v2, v47, v2
	global_store_short_d16_hi v[0:1], v3, off offset:192
	v_bfe_u32 v3, v2, 16, 1
	v_add3_u32 v2, v2, v3, s52
	global_store_short_d16_hi v[0:1], v2, off offset:224
	global_load_dwordx4 v[216:219], v[138:139], off
	global_load_dwordx4 v[220:223], v[138:139], off offset:16
	global_load_dwordx4 v[224:227], v[138:139], off offset:2048
	global_load_dwordx4 v[228:231], v[138:139], off offset:2064
	global_load_dwordx4 v[232:235], v[140:141], off
	global_load_dwordx4 v[236:239], v[140:141], off offset:16
	v_readfirstlane_b32 s8, v185
	s_nop 3
	s_add_u32 s8, s8, s68
	s_add_u32 s100, s8, s67
	s_add_i32 s6, s100, -2
	s_mul_i32 s6, s6, 0xc00
	s_ashr_i32 s7, s6, 31
	s_add_u32 s96, s60, s6
	s_addc_u32 s97, s61, s7
	s_add_u32 s96, s96, 0xb7a0000
	s_addc_u32 s97, s97, 0
	s_lshl_b32 s6, s100, 11
	s_add_u32 s98, s60, s6
	s_addc_u32 s99, s61, 0
	s_add_u32 s98, s98, 0x67a0000
	s_addc_u32 s99, s99, 0
	global_load_dwordx4 v[0:3], v146, s[96:97] offset:1024
	global_load_dwordx4 v[4:7], v146, s[96:97] offset:2048
	s_add_u32 s96, s96, 0xc00
	s_addc_u32 s97, s97, 0
	global_load_dwordx4 v[8:11], v146, s[96:97] offset:1024
	global_load_dwordx4 v[12:15], v146, s[96:97] offset:2048
	s_add_u32 s96, s96, 0xc00
	s_addc_u32 s97, s97, 0
	global_load_dwordx4 v[16:19], v146, s[96:97] offset:1024
	global_load_dwordx4 v[20:23], v146, s[96:97] offset:2048
	global_load_dwordx4 v[80:83], v146, s[96:97]
	s_add_u32 s96, s96, 0xc00
	s_addc_u32 s97, s97, 0
	global_load_dwordx4 v[24:27], v146, s[96:97] offset:1024
	global_load_dwordx4 v[28:31], v146, s[96:97] offset:2048
	global_load_dwordx4 v[84:87], v146, s[96:97]
	s_add_u32 s96, s96, 0xc00
	s_addc_u32 s97, s97, 0
	global_load_dwordx4 v[32:35], v146, s[96:97] offset:1024
	global_load_dwordx4 v[36:39], v146, s[96:97] offset:2048
	global_load_dwordx4 v[88:91], v146, s[96:97]
	s_add_u32 s96, s96, 0xc00
	s_addc_u32 s97, s97, 0
	global_load_dwordx4 v[40:43], v146, s[96:97] offset:1024
	global_load_dwordx4 v[44:47], v146, s[96:97] offset:2048
	global_load_dwordx4 v[92:95], v146, s[96:97]
	s_add_u32 s96, s96, 0xc00
	s_addc_u32 s97, s97, 0
	global_load_dwordx4 v[48:51], v146, s[96:97] offset:1024
	global_load_dwordx4 v[52:55], v146, s[96:97] offset:2048
	global_load_dwordx4 v[96:99], v146, s[96:97]
	s_add_u32 s96, s96, 0xc00
	s_addc_u32 s97, s97, 0
	global_load_dwordx4 v[56:59], v146, s[96:97] offset:1024
	global_load_dwordx4 v[60:63], v146, s[96:97] offset:2048
	global_load_dwordx4 v[100:103], v146, s[96:97]
	s_add_u32 s96, s96, 0xc00
	s_addc_u32 s97, s97, 0
	global_load_dwordx4 v[64:67], v146, s[96:97] offset:1024
	global_load_dwordx4 v[68:71], v146, s[96:97] offset:2048
	global_load_dwordx4 v[104:107], v146, s[96:97]
	s_add_u32 s96, s96, 0xc00
	s_addc_u32 s97, s97, 0
	global_load_dwordx4 v[72:75], v146, s[96:97] offset:1024
	global_load_dwordx4 v[76:79], v146, s[96:97] offset:2048
	global_load_dwordx4 v[108:111], v146, s[96:97]
	s_waitcnt vmcnt(0)
	s_cmp_lg_u32 s8, 0
	s_cbranch_scc1 .Lconv_nz
	v_mov_b32_e32 v0, 0
	v_mov_b32_e32 v1, 0
	v_mov_b32_e32 v2, 0
	v_mov_b32_e32 v3, 0
	v_mov_b32_e32 v4, 0
	v_mov_b32_e32 v5, 0
	v_mov_b32_e32 v6, 0
	v_mov_b32_e32 v7, 0
	v_mov_b32_e32 v8, 0
	v_mov_b32_e32 v9, 0
	v_mov_b32_e32 v10, 0
	v_mov_b32_e32 v11, 0
	v_mov_b32_e32 v12, 0
	v_mov_b32_e32 v13, 0
	v_mov_b32_e32 v14, 0
	v_mov_b32_e32 v15, 0
